# waits removed in zeroing blocks; attention K-frag prefetch + PV double buffering; SSD scan via DPP
# speedup vs baseline: 1.1745x; 1.1745x over previous
; #define LAS __attribute__((address_space(3)))
; __global__ void __launch_bounds__(NWAVES * 64, 2) trunk_fwd(Args args) {
;     extern __shared__ __attribute__((aligned(16))) unsigned char lds_raw[];
;     Frame F;
;     F.lds = (LAS unsigned char*)lds_raw;
;     F.tid = threadIdx.x; F.lane = F.tid & 63; F.wave = __builtin_amdgcn_readfirstlane(F.tid >> 6);
;     F.G = gridDim.x; { const int bx = blockIdx.x; F.vcu = (F.G % 8 == 0) ? (bx % 8) * (F.G / 8) + bx / 8 : bx; }
;     F.gw = F.vcu * NWAVES + F.wave; F.NGW = F.G * NWAVES;
_Z9trunk_fwd4Args:
	s_load_dword s82, s[0:1], 0x118
	s_mov_b32 s95, s2
	s_add_u32 s2, s0, 0x118
	s_addc_u32 s3, s1, 0
	s_mov_b32 s62, s95
	v_writelane_b32 v252, s2, 0
	s_nop 1
	v_writelane_b32 v252, s3, 1
	s_waitcnt lgkmcnt(0)
	s_and_b32 s2, s82, 7
	s_cmp_lg_u32 s2, 0
	s_cbranch_scc1 .LBB0_2
	s_ashr_i32 s3, s95, 31
	s_lshr_b32 s3, s3, 29
	s_add_i32 s3, s95, s3
	s_and_b32 s4, s3, -8
	s_ashr_i32 s2, s82, 3
	s_sub_i32 s4, s95, s4
	s_mul_i32 s2, s2, s4
	s_ashr_i32 s3, s3, 3
	s_add_i32 s62, s2, s3

; #define PG8_LDA(dst, b, h) do { _Pragma("unroll") for (int m = 0; m < 4; ++m) _Pragma("unroll") for (int k = 0; k < 2; ++k) dst[m][k] = *(const LAS bf16x8*)(lds + PG8_SA(b, h) + aoff + m * 2048 + k * 1024); } while (0)
; #define PG8_BAR __builtin_amdgcn_s_barrier()
;     ...
;         const bool has_next = S.next(ui + 1, nxt);
;         const char* nA = PG8_UNI(has_next ? nxt.a : cA); const char* nB = PG8_UNI(has_next ? nxt.b : cB);
;         const int nt = cur.kt;
;         for (int t = 0; t < nt; t += 2) {
;             const bool last = (t == nt - 2);
;             if constexpr (HOOK) { if (t == 16 || t == 32) E.mid(acc, cur, t >> 4, wr, wc); }
;             const char* a1 = cA + (size_t)(t + 1) * kstepA;
;             const char* a2 = last ? nA : cA + (size_t)(t + 2) * kstepA; const char* b2 = last ? nB : cB + (size_t)(t + 2) * kstep;
;             const char* a3 = a2 + kstepA; const char* b3 = b2 + kstep;
;             PG8_LDB(B0, 0, 0); PG8_LDB(B1, 0, 1); PG8_SCHED; PG8_LDA(At, 0, 0); PG8_STAGE(PG8_SA(1, 1), a1 + hstepA, voffA);
;             PG8_WAIT_V(8); PG8_WAIT_L(0); PG8_BAR; PG8_MMA(0, 0, At, B0); PG8_MMA(0, 1, At, B1); PG8_BAR; PG8_SCHED;
;             PG8_LDA(At, 0, 1); PG8_STAGE(PG8_SB(0, 0), b2, voffB); PG8_STAGE(PG8_SB(0, 1), b2 + hstepB, voffB); PG8_STAGE(PG8_SA(0, 0), a2, voffA);
;             PG8_WAIT_V(8); PG8_WAIT_L(0); PG8_BAR; PG8_MMA(1, 0, At, B0); PG8_MMA(1, 1, At, B1); PG8_BAR; PG8_SCHED;
;             PG8_LDB(B0, 1, 0); PG8_LDB(B1, 1, 1); PG8_SCHED; PG8_LDA(At, 1, 0); PG8_STAGE(PG8_SA(0, 1), a2 + hstepA, voffA);
;             PG8_WAIT_V(8); PG8_WAIT_L(0); PG8_BAR; PG8_MMA(0, 0, At, B0); PG8_MMA(0, 1, At, B1); PG8_BAR; PG8_SCHED;
;             PG8_LDA(At, 1, 1); PG8_STAGE(PG8_SB(1, 0), b3, voffB); PG8_STAGE(PG8_SB(1, 1), b3 + hstepB, voffB); PG8_STAGE(PG8_SA(1, 0), a3, voffA);
;             PG8_WAIT_V(8); PG8_WAIT_L(0); PG8_BAR; PG8_MMA(1, 0, At, B0); PG8_MMA(1, 1, At, B1); PG8_BAR; PG8_SCHED;
;         }
;         if (wr == 0) PG8_BAR;
;         E(acc, cur, wr, wc, fr, fq);
;         if (!has_next) break;
; #pragma unroll
;         for (int a = 0; a < 2; ++a)
; #pragma unroll
;             for (int b = 0; b < 2; ++b)
; #pragma unroll
;                 for (int m = 0; m < 4; ++m)
; #pragma unroll
;                     for (int n = 0; n < 2; ++n) acc[a][b][m][n] = (f32x4){0.f, 0.f, 0.f, 0.f};
;         cur = nxt; cA = nA; cB = nB; ++ui;
.LBB0_511:
	v_mov_b32_e32 v2, s24
	v_cndmask_b32_e64 v2, v2, v134, s[16:17]
	v_mov_b32_e32 v3, s25
	s_add_i32 s15, s55, -2
	v_cndmask_b32_e64 v3, v3, v135, s[16:17]
	v_readfirstlane_b32 s18, v2
	v_mov_b32_e32 v2, s26
	s_add_u32 s56, s26, 0x100
	v_readfirstlane_b32 s19, v3
	v_cndmask_b32_e64 v2, v2, v136, s[16:17]
	v_mov_b32_e32 v3, s27
	s_addc_u32 s57, s27, 0
	v_cndmask_b32_e64 v3, v3, v137, s[16:17]
	v_readfirstlane_b32 s20, v2
	s_add_u32 s24, s24, 0x80080
	v_mov_b32_e32 v2, 0
	v_readfirstlane_b32 s21, v3
	s_addc_u32 s25, s25, 0
	s_mov_b32 s26, 0
	v_mov_b32_e32 v3, v2
	v_mov_b32_e32 v4, v2
	v_mov_b32_e32 v5, v2
	v_mov_b32_e32 v6, v2
	v_mov_b32_e32 v7, v2
	v_mov_b32_e32 v8, v2
	v_mov_b32_e32 v9, v2
	v_mov_b32_e32 v18, v2
	v_mov_b32_e32 v19, v2
	v_mov_b32_e32 v20, v2
	v_mov_b32_e32 v21, v2
	v_mov_b32_e32 v22, v2
	v_mov_b32_e32 v23, v2
	v_mov_b32_e32 v24, v2
	v_mov_b32_e32 v25, v2
	v_mov_b32_e32 v34, v2
	v_mov_b32_e32 v35, v2
	v_mov_b32_e32 v36, v2
	v_mov_b32_e32 v37, v2
	v_mov_b32_e32 v38, v2
	v_mov_b32_e32 v39, v2
	v_mov_b32_e32 v40, v2
	v_mov_b32_e32 v41, v2
	v_mov_b32_e32 v50, v2
	v_mov_b32_e32 v51, v2
	v_mov_b32_e32 v52, v2
	v_mov_b32_e32 v53, v2
	v_mov_b32_e32 v54, v2
	v_mov_b32_e32 v55, v2
	v_mov_b32_e32 v56, v2
	v_mov_b32_e32 v57, v2
	v_mov_b32_e32 v10, v2
	v_mov_b32_e32 v11, v2
	v_mov_b32_e32 v12, v2
	v_mov_b32_e32 v13, v2
	v_mov_b32_e32 v14, v2
	v_mov_b32_e32 v15, v2
	v_mov_b32_e32 v16, v2
	v_mov_b32_e32 v17, v2
	v_mov_b32_e32 v26, v2
	v_mov_b32_e32 v27, v2
	v_mov_b32_e32 v28, v2
	v_mov_b32_e32 v29, v2
	v_mov_b32_e32 v30, v2
	v_mov_b32_e32 v31, v2
	v_mov_b32_e32 v32, v2
	v_mov_b32_e32 v33, v2
	v_mov_b32_e32 v42, v2
	v_mov_b32_e32 v43, v2
	v_mov_b32_e32 v44, v2
	v_mov_b32_e32 v45, v2
	v_mov_b32_e32 v46, v2
	v_mov_b32_e32 v47, v2
	v_mov_b32_e32 v48, v2
	v_mov_b32_e32 v49, v2
	v_mov_b32_e32 v58, v2
	v_mov_b32_e32 v59, v2
	v_mov_b32_e32 v60, v2
	v_mov_b32_e32 v61, v2
	v_mov_b32_e32 v62, v2
	v_mov_b32_e32 v63, v2
	v_mov_b32_e32 v64, v2
	v_mov_b32_e32 v65, v2
	v_mov_b32_e32 v66, v2
	v_mov_b32_e32 v67, v2
	v_mov_b32_e32 v68, v2
	v_mov_b32_e32 v69, v2
	v_mov_b32_e32 v70, v2
	v_mov_b32_e32 v71, v2
	v_mov_b32_e32 v72, v2
	v_mov_b32_e32 v73, v2
	v_mov_b32_e32 v82, v2
	v_mov_b32_e32 v83, v2
	v_mov_b32_e32 v84, v2
	v_mov_b32_e32 v85, v2
	v_mov_b32_e32 v86, v2
	v_mov_b32_e32 v87, v2
	v_mov_b32_e32 v88, v2
	v_mov_b32_e32 v89, v2
	v_mov_b32_e32 v98, v2
	v_mov_b32_e32 v99, v2
	v_mov_b32_e32 v100, v2
	v_mov_b32_e32 v101, v2
	v_mov_b32_e32 v102, v2
	v_mov_b32_e32 v103, v2
	v_mov_b32_e32 v104, v2
	v_mov_b32_e32 v105, v2
	v_mov_b32_e32 v114, v2
	v_mov_b32_e32 v115, v2
	v_mov_b32_e32 v116, v2
	v_mov_b32_e32 v117, v2
	v_mov_b32_e32 v118, v2
	v_mov_b32_e32 v119, v2
	v_mov_b32_e32 v120, v2
	v_mov_b32_e32 v121, v2
	v_mov_b32_e32 v74, v2
	v_mov_b32_e32 v75, v2
	v_mov_b32_e32 v76, v2
	v_mov_b32_e32 v77, v2
	v_mov_b32_e32 v78, v2
	v_mov_b32_e32 v79, v2
	v_mov_b32_e32 v80, v2
	v_mov_b32_e32 v81, v2
	v_mov_b32_e32 v90, v2
	v_mov_b32_e32 v91, v2
	v_mov_b32_e32 v92, v2
	v_mov_b32_e32 v93, v2
	v_mov_b32_e32 v94, v2
	v_mov_b32_e32 v95, v2
	v_mov_b32_e32 v96, v2
	v_mov_b32_e32 v97, v2
	v_mov_b32_e32 v106, v2
	v_mov_b32_e32 v107, v2
	v_mov_b32_e32 v108, v2
	v_mov_b32_e32 v109, v2
	v_mov_b32_e32 v110, v2
	v_mov_b32_e32 v111, v2
	v_mov_b32_e32 v112, v2
	v_mov_b32_e32 v113, v2
	v_mov_b32_e32 v122, v2
	v_mov_b32_e32 v123, v2
	v_mov_b32_e32 v124, v2
	v_mov_b32_e32 v125, v2
	v_mov_b32_e32 v126, v2
	v_mov_b32_e32 v127, v2
	v_mov_b32_e32 v128, v2
	v_mov_b32_e32 v129, v2

;     __device__ __forceinline__ bool next(int i, Unit& u) const {
;         const long L = (long)i * G + c;
;         if (L < nwg) { xcd_remap((int)L, nM, nN, u.pm, u.pn); if (latonly) u.pm += (u.pm >> 4) + 1; u.aux = 0; u.kt = kt; u.a = A + (size_t)u.pm * tA; u.b = B + (size_t)u.pn * tB; return true; }
;         const int x = (int)(L - nwg); if (x >= nctx) return false;
;         if (cproj) {
;             const int p = x / 20, t2 = x - 20 * p; u.pm = PPB_ * p; u.pn = (t2 < 8) ? 4 + t2 : 8 + t2; u.aux = 0; u.kt = kt; u.a = A + (size_t)u.pm * tA; u.b = B + (size_t)u.pn * tB; return true; }
;         const int q = x & 3, t2 = x >> 2; u.pm = PPB_ * (t2 / nN); u.pn = t2 % nN; u.aux = 1 + q; u.kt = kt >> 2;
;         u.a = A + (size_t)u.pm * tA + (size_t)q * (kt >> 2) * BK * 2; u.b = B + (size_t)u.pn * tB + (size_t)q * (kt >> 2) * BK * 2; return true;
;     }
; __global__ void __launch_bounds__(NWAVES * 64, 2) trunk_fwd(Args args) {
;     ...
;             PH_BEGIN
;                 pg8::Gemm g{D, D, D}; pg8::StaticOrder S;
;                 if (l == 0) S.init(NPAN, LDP / 256, F.G, (int)blockIdx.x, HM, D, (const bf16_t*)(WGT + W_IN), D, D);
;                 else { S.init(64, LDP / 256, F.G, (int)blockIdx.x, HM, D, (const bf16_t*)(WGT + W_IN), D, D, 1, 80); S.cproj = 1; }
;                 EpiProj E{PROJ, (float*)(ws + WS_DT), ROPEC, ROPES, (bf16_t*)(ws + WS_O), (unsigned*)(ws + WS_KM) + l * 512};
;                 pg8::gemm_phase<EpiProj, pg8::StaticOrder>(F.lds + RING_OFF, g, S, E, F.tid);
.LBB0_578:
	s_andn2_b64 vcc, exec, s[0:1]
	v_readlane_b32 s22, v254, 45
	v_readlane_b32 s23, v254, 46
	s_cbranch_vccnz .LBB0_916
	s_mov_b64 s[14:15], s[90:91]
	s_cmp_gt_u32 s22, 2
	v_mbcnt_lo_u32_b32 v239, -1, 0
	v_mbcnt_hi_u32_b32 v239, -1, v239
	s_cselect_b64 s[16:17], -1, 0
	s_add_u32 s62, s14, 0x9a00000
	s_addc_u32 s63, s15, 0
	s_add_u32 s64, s14, 0x3e800000
	s_addc_u32 s65, s15, 0
	s_cmp_lt_u32 s22, 3
	s_cselect_b64 s[18:19], -1, 0
	s_and_b64 s[0:1], s[18:19], exec
	s_movk_i32 s0, 0xdd0
	v_add_u32_e32 v0, s83, v239
	s_cselect_b32 s92, s0, 0xd00
	v_readfirstlane_b32 s8, v0
	s_cselect_b32 s66, 0x44, 64
	s_cselect_b32 s67, 0, 0x50
	s_cmp_ge_i32 s95, s92
	s_mov_b64 s[0:1], -1
	s_cbranch_scc0 .LBB0_586
	s_sub_i32 s9, s95, s92
	s_mov_b64 s[0:1], 0
	s_cmp_ge_i32 s9, s67
	s_mov_b64 s[6:7], 0
	s_cbranch_scc1 .LBB0_586
	s_andn2_b64 vcc, exec, s[16:17]
	s_mov_b64 s[6:7], -1
	s_cbranch_vccnz .LBB0_583
	s_mul_i32 s2, s9, 0x6667
	s_lshr_b32 s3, s2, 31
	s_ashr_i32 s2, s2, 19
	s_add_i32 s2, s2, s3
	s_mul_i32 s3, s2, 0xffffffec
	s_add_i32 s3, s3, s9
	s_mul_i32 s54, s2, 17
	s_cmp_lt_i32 s3, 8
	s_cselect_b32 s2, 4, 8
	s_ashr_i32 s55, s54, 31
	s_add_i32 s56, s2, s3
	s_lshl_b64 s[2:3], s[54:55], 20
	s_add_u32 s2, s62, s2
	s_addc_u32 s3, s63, s3
	s_ashr_i32 s57, s56, 31
	s_lshl_b64 s[4:5], s[56:57], 20
	s_add_u32 s4, s64, s4
	s_addc_u32 s5, s65, s5
	s_mov_b64 s[6:7], 0

; #define PG8_LDA(dst, b, h) do { _Pragma("unroll") for (int m = 0; m < 4; ++m) _Pragma("unroll") for (int k = 0; k < 2; ++k) dst[m][k] = *(const LAS bf16x8*)(lds + PG8_SA(b, h) + aoff + m * 2048 + k * 1024); } while (0)
; #define PG8_BAR __builtin_amdgcn_s_barrier()
;     ...
;         const bool has_next = S.next(ui + 1, nxt);
;         const char* nA = PG8_UNI(has_next ? nxt.a : cA); const char* nB = PG8_UNI(has_next ? nxt.b : cB);
;         const int nt = cur.kt;
;         for (int t = 0; t < nt; t += 2) {
;             const bool last = (t == nt - 2);
;             if constexpr (HOOK) { if (t == 16 || t == 32) E.mid(acc, cur, t >> 4, wr, wc); }
;             const char* a1 = cA + (size_t)(t + 1) * kstepA;
;             const char* a2 = last ? nA : cA + (size_t)(t + 2) * kstepA; const char* b2 = last ? nB : cB + (size_t)(t + 2) * kstep;
;             const char* a3 = a2 + kstepA; const char* b3 = b2 + kstep;
;             PG8_LDB(B0, 0, 0); PG8_LDB(B1, 0, 1); PG8_SCHED; PG8_LDA(At, 0, 0); PG8_STAGE(PG8_SA(1, 1), a1 + hstepA, voffA);
;             PG8_WAIT_V(8); PG8_WAIT_L(0); PG8_BAR; PG8_MMA(0, 0, At, B0); PG8_MMA(0, 1, At, B1); PG8_BAR; PG8_SCHED;
;             PG8_LDA(At, 0, 1); PG8_STAGE(PG8_SB(0, 0), b2, voffB); PG8_STAGE(PG8_SB(0, 1), b2 + hstepB, voffB); PG8_STAGE(PG8_SA(0, 0), a2, voffA);
;             PG8_WAIT_V(8); PG8_WAIT_L(0); PG8_BAR; PG8_MMA(1, 0, At, B0); PG8_MMA(1, 1, At, B1); PG8_BAR; PG8_SCHED;
;             PG8_LDB(B0, 1, 0); PG8_LDB(B1, 1, 1); PG8_SCHED; PG8_LDA(At, 1, 0); PG8_STAGE(PG8_SA(0, 1), a2 + hstepA, voffA);
;             PG8_WAIT_V(8); PG8_WAIT_L(0); PG8_BAR; PG8_MMA(0, 0, At, B0); PG8_MMA(0, 1, At, B1); PG8_BAR; PG8_SCHED;
;             PG8_LDA(At, 1, 1); PG8_STAGE(PG8_SB(1, 0), b3, voffB); PG8_STAGE(PG8_SB(1, 1), b3 + hstepB, voffB); PG8_STAGE(PG8_SA(1, 0), a3, voffA);
;             PG8_WAIT_V(8); PG8_WAIT_L(0); PG8_BAR; PG8_MMA(1, 0, At, B0); PG8_MMA(1, 1, At, B1); PG8_BAR; PG8_SCHED;
;         }
;         if (wr == 0) PG8_BAR;
;         E(acc, cur, wr, wc, fr, fq);
;         if (!has_next) break;
; #pragma unroll
;         for (int a = 0; a < 2; ++a)
; #pragma unroll
;             for (int b = 0; b < 2; ++b)
; #pragma unroll
;                 for (int m = 0; m < 4; ++m)
; #pragma unroll
;                     for (int n = 0; n < 2; ++n) acc[a][b][m][n] = (f32x4){0.f, 0.f, 0.f, 0.f};
;         cur = nxt; cA = nA; cB = nB; ++ui;
.LBB0_603:
	s_and_b64 s[6:7], s[48:49], exec
	s_cselect_b32 s50, s44, s2
	s_cselect_b32 s51, s45, s3
	s_cselect_b32 s52, s46, s4
	s_cselect_b32 s53, s47, s5
	s_add_i32 s10, s12, -2
	s_add_u32 s11, s4, 0x100
	s_addc_u32 s13, s5, 0
	s_add_u32 s2, s2, 0x80080
	v_mov_b32_e32 v34, 0
	s_addc_u32 s3, s3, 0
	s_mov_b32 s4, 0
	v_mov_b32_e32 v35, v34
	v_mov_b32_e32 v36, v34
	v_mov_b32_e32 v37, v34
	v_mov_b32_e32 v70, v34
	v_mov_b32_e32 v71, v34
	v_mov_b32_e32 v72, v34
	v_mov_b32_e32 v73, v34
	v_mov_b32_e32 v74, v34
	v_mov_b32_e32 v75, v34
	v_mov_b32_e32 v76, v34
	v_mov_b32_e32 v77, v34
	v_mov_b32_e32 v78, v34
	v_mov_b32_e32 v79, v34
	v_mov_b32_e32 v80, v34
	v_mov_b32_e32 v81, v34
	v_mov_b32_e32 v82, v34
	v_mov_b32_e32 v83, v34
	v_mov_b32_e32 v84, v34
	v_mov_b32_e32 v85, v34
	v_mov_b32_e32 v86, v34
	v_mov_b32_e32 v87, v34
	v_mov_b32_e32 v88, v34
	v_mov_b32_e32 v89, v34
	v_mov_b32_e32 v90, v34
	v_mov_b32_e32 v91, v34
	v_mov_b32_e32 v92, v34
	v_mov_b32_e32 v93, v34
	v_mov_b32_e32 v94, v34
	v_mov_b32_e32 v95, v34
	v_mov_b32_e32 v96, v34
	v_mov_b32_e32 v97, v34
	v_mov_b32_e32 v2, v34
	v_mov_b32_e32 v3, v34
	v_mov_b32_e32 v4, v34
	v_mov_b32_e32 v5, v34
	v_mov_b32_e32 v6, v34
	v_mov_b32_e32 v7, v34
	v_mov_b32_e32 v8, v34
	v_mov_b32_e32 v9, v34
	v_mov_b32_e32 v10, v34
	v_mov_b32_e32 v11, v34
	v_mov_b32_e32 v12, v34
	v_mov_b32_e32 v13, v34
	v_mov_b32_e32 v14, v34
	v_mov_b32_e32 v15, v34
	v_mov_b32_e32 v16, v34
	v_mov_b32_e32 v17, v34
	v_mov_b32_e32 v18, v34
	v_mov_b32_e32 v19, v34
	v_mov_b32_e32 v20, v34
	v_mov_b32_e32 v21, v34
	v_mov_b32_e32 v22, v34
	v_mov_b32_e32 v23, v34
	v_mov_b32_e32 v24, v34
	v_mov_b32_e32 v25, v34
	v_mov_b32_e32 v26, v34
	v_mov_b32_e32 v27, v34
	v_mov_b32_e32 v28, v34
	v_mov_b32_e32 v29, v34
	v_mov_b32_e32 v30, v34
	v_mov_b32_e32 v31, v34
	v_mov_b32_e32 v32, v34
	v_mov_b32_e32 v33, v34
	v_mov_b32_e32 v98, v34
	v_mov_b32_e32 v99, v34
	v_mov_b32_e32 v100, v34
	v_mov_b32_e32 v101, v34
	v_mov_b32_e32 v102, v34
	v_mov_b32_e32 v103, v34
	v_mov_b32_e32 v104, v34
	v_mov_b32_e32 v105, v34
	v_mov_b32_e32 v106, v34
	v_mov_b32_e32 v107, v34
	v_mov_b32_e32 v108, v34
	v_mov_b32_e32 v109, v34
	v_mov_b32_e32 v110, v34
	v_mov_b32_e32 v111, v34
	v_mov_b32_e32 v112, v34
	v_mov_b32_e32 v113, v34
	v_mov_b32_e32 v114, v34
	v_mov_b32_e32 v115, v34
	v_mov_b32_e32 v116, v34
	v_mov_b32_e32 v117, v34
	v_mov_b32_e32 v118, v34
	v_mov_b32_e32 v119, v34
	v_mov_b32_e32 v120, v34
	v_mov_b32_e32 v121, v34
	v_mov_b32_e32 v122, v34
	v_mov_b32_e32 v123, v34
	v_mov_b32_e32 v124, v34
	v_mov_b32_e32 v125, v34
	v_mov_b32_e32 v126, v34
	v_mov_b32_e32 v127, v34
	v_mov_b32_e32 v128, v34
	v_mov_b32_e32 v129, v34
	v_mov_b32_e32 v38, v34
	v_mov_b32_e32 v39, v34
	v_mov_b32_e32 v40, v34
	v_mov_b32_e32 v41, v34
	v_mov_b32_e32 v42, v34
	v_mov_b32_e32 v43, v34
	v_mov_b32_e32 v44, v34
	v_mov_b32_e32 v45, v34
	v_mov_b32_e32 v46, v34
	v_mov_b32_e32 v47, v34
	v_mov_b32_e32 v48, v34
	v_mov_b32_e32 v49, v34
	v_mov_b32_e32 v50, v34
	v_mov_b32_e32 v51, v34
	v_mov_b32_e32 v52, v34
	v_mov_b32_e32 v53, v34
	v_mov_b32_e32 v54, v34
	v_mov_b32_e32 v55, v34
	v_mov_b32_e32 v56, v34
	v_mov_b32_e32 v57, v34
	v_mov_b32_e32 v58, v34
	v_mov_b32_e32 v59, v34
	v_mov_b32_e32 v60, v34
	v_mov_b32_e32 v61, v34
	v_mov_b32_e32 v62, v34
	v_mov_b32_e32 v63, v34
	v_mov_b32_e32 v64, v34
	v_mov_b32_e32 v65, v34
	v_mov_b32_e32 v66, v34
	v_mov_b32_e32 v67, v34
	v_mov_b32_e32 v68, v34
	v_mov_b32_e32 v69, v34
.LBB0_604:
	v_add_u32_e32 v0, 0x10000, v244
	ds_read_b128 v[130:133], v0
	ds_read_b128 v[134:137], v0 offset:1024
	ds_read_b128 v[138:141], v0 offset:2048
	ds_read_b128 v[142:145], v0 offset:3072
	v_add_u32_e32 v0, 0x14000, v244
	ds_read_b128 v[146:149], v0
	ds_read_b128 v[150:153], v0 offset:1024
	ds_read_b128 v[154:157], v0 offset:2048
	ds_read_b128 v[158:161], v0 offset:3072
	s_add_i32 s43, s4, 2
	s_add_u32 s5, s2, 0xfff80080
	s_addc_u32 s6, s3, -1
	s_cmp_eq_u32 s10, s4
	s_cselect_b32 s8, s50, s5
	s_cselect_b32 s9, s51, s6
	s_cselect_b32 s6, s52, s11
	s_cselect_b32 s7, s53, s13
	s_add_u32 s4, s8, 0x80
	s_addc_u32 s5, s9, 0
	ds_read_b128 v[162:165], v245
	ds_read_b128 v[166:169], v245 offset:1024
	ds_read_b128 v[170:173], v245 offset:2048
	ds_read_b128 v[174:177], v245 offset:3072
	ds_read_b128 v[178:181], v245 offset:4096
	ds_read_b128 v[182:185], v245 offset:5120
	ds_read_b128 v[186:189], v245 offset:6144
	ds_read_b128 v[190:193], v245 offset:7168
	s_mov_b32 m0, s86
	s_nop 0
	global_load_lds_dwordx4 v240, s[2:3]
	s_mov_b32 m0, s91
	s_nop 0
	global_load_lds_dwordx4 v242, s[2:3]
	s_waitcnt vmcnt(8)
	s_waitcnt lgkmcnt(0)
	s_barrier
; #define PG8_LDA(dst, b, h) do { _Pragma("unroll") for (int m = 0; m < 4; ++m) _Pragma("unroll") for (int k = 0; k < 2; ++k) dst[m][k] = *(const LAS bf16x8*)(lds + PG8_SA(b, h) + aoff + m * 2048 + k * 1024); } while (0)
; #define PG8_LDB(dst, b, h) do { _Pragma("unroll") for (int n = 0; n < 2; ++n) _Pragma("unroll") for (int k = 0; k < 2; ++k) dst[n][k] = *(const LAS bf16x8*)(lds + PG8_SB(b, h) + boff + n * 2048 + k * 1024); } while (0)
; #define PG8_MMA(ai, bj, At, Bt) do { __builtin_amdgcn_s_setprio(1); _Pragma("unroll") for (int m = 0; m < 4; ++m) _Pragma("unroll") for (int n = 0; n < 2; ++n) _Pragma("unroll") for (int k = 0; k < 2; ++k) \
;         acc[ai][bj][m][n] = __builtin_amdgcn_mfma_f32_16x16x32_bf16(Bt[n][k], At[m][k], acc[ai][bj][m][n], 0, 0, 0); __builtin_amdgcn_s_setprio(0); } while (0)
; #define PG8_WAIT_V(n) asm volatile("s_waitcnt vmcnt(" #n ")" ::: "memory")
; #define PG8_WAIT_L(n) asm volatile("s_waitcnt lgkmcnt(" #n ")" ::: "memory")
; #define PG8_BAR __builtin_amdgcn_s_barrier()
; #define PG8_SCHED __builtin_amdgcn_sched_barrier(0)
;     ...
;             PG8_LDB(B0, 0, 0); PG8_LDB(B1, 0, 1); PG8_SCHED; PG8_LDA(At, 0, 0); PG8_STAGE(PG8_SA(1, 1), a1 + hstepA, voffA);
;             PG8_WAIT_V(8); PG8_WAIT_L(0); PG8_BAR; PG8_MMA(0, 0, At, B0); PG8_MMA(0, 1, At, B1); PG8_BAR; PG8_SCHED;
;             PG8_LDA(At, 0, 1); PG8_STAGE(PG8_SB(0, 0), b2, voffB); PG8_STAGE(PG8_SB(0, 1), b2 + hstepB, voffB); PG8_STAGE(PG8_SA(0, 0), a2, voffA);
;             PG8_WAIT_V(8); PG8_WAIT_L(0); PG8_BAR; PG8_MMA(1, 0, At, B0); PG8_MMA(1, 1, At, B1); PG8_BAR; PG8_SCHED;
	s_setprio 1
	s_waitcnt lgkmcnt(7)
	v_mfma_f32_16x16x32_bf16 v[66:69], v[130:133], v[162:165], v[66:69]
	v_mfma_f32_16x16x32_bf16 v[62:65], v[138:141], v[162:165], v[62:65]
	s_waitcnt lgkmcnt(5)
	v_mfma_f32_16x16x32_bf16 v[58:61], v[130:133], v[170:173], v[58:61]
	v_mfma_f32_16x16x32_bf16 v[54:57], v[138:141], v[170:173], v[54:57]
	s_waitcnt lgkmcnt(3)
	v_mfma_f32_16x16x32_bf16 v[50:53], v[130:133], v[178:181], v[50:53]
	v_mfma_f32_16x16x32_bf16 v[46:49], v[138:141], v[178:181], v[46:49]
	s_waitcnt lgkmcnt(1)
	v_mfma_f32_16x16x32_bf16 v[42:45], v[130:133], v[186:189], v[42:45]
	v_mfma_f32_16x16x32_bf16 v[38:41], v[138:141], v[186:189], v[38:41]
	v_mfma_f32_16x16x32_bf16 v[66:69], v[134:137], v[166:169], v[66:69]
	v_mfma_f32_16x16x32_bf16 v[62:65], v[142:145], v[166:169], v[62:65]
	v_mfma_f32_16x16x32_bf16 v[58:61], v[134:137], v[174:177], v[58:61]
	v_mfma_f32_16x16x32_bf16 v[54:57], v[142:145], v[174:177], v[54:57]
	v_mfma_f32_16x16x32_bf16 v[50:53], v[134:137], v[182:185], v[50:53]
	v_mfma_f32_16x16x32_bf16 v[46:49], v[142:145], v[182:185], v[46:49]
	s_waitcnt lgkmcnt(0)
	v_mfma_f32_16x16x32_bf16 v[42:45], v[134:137], v[190:193], v[42:45]
	v_mfma_f32_16x16x32_bf16 v[38:41], v[142:145], v[190:193], v[38:41]
	s_setprio 0
	s_setprio 1
	v_mfma_f32_16x16x32_bf16 v[126:129], v[146:149], v[162:165], v[126:129]
	v_mfma_f32_16x16x32_bf16 v[122:125], v[154:157], v[162:165], v[122:125]
	v_mfma_f32_16x16x32_bf16 v[118:121], v[146:149], v[170:173], v[118:121]
	v_mfma_f32_16x16x32_bf16 v[114:117], v[154:157], v[170:173], v[114:117]
	v_mfma_f32_16x16x32_bf16 v[110:113], v[146:149], v[178:181], v[110:113]
	v_mfma_f32_16x16x32_bf16 v[106:109], v[154:157], v[178:181], v[106:109]
	v_mfma_f32_16x16x32_bf16 v[102:105], v[146:149], v[186:189], v[102:105]
	v_mfma_f32_16x16x32_bf16 v[98:101], v[154:157], v[186:189], v[98:101]
	v_mfma_f32_16x16x32_bf16 v[126:129], v[150:153], v[166:169], v[126:129]
	v_mfma_f32_16x16x32_bf16 v[122:125], v[158:161], v[166:169], v[122:125]
	v_mfma_f32_16x16x32_bf16 v[118:121], v[150:153], v[174:177], v[118:121]
	v_mfma_f32_16x16x32_bf16 v[114:117], v[158:161], v[174:177], v[114:117]
	v_mfma_f32_16x16x32_bf16 v[110:113], v[150:153], v[182:185], v[110:113]
	v_mfma_f32_16x16x32_bf16 v[106:109], v[158:161], v[182:185], v[106:109]
	v_mfma_f32_16x16x32_bf16 v[102:105], v[150:153], v[190:193], v[102:105]
	v_mfma_f32_16x16x32_bf16 v[98:101], v[158:161], v[190:193], v[98:101]
	s_setprio 0
	s_barrier
	ds_read_b128 v[162:165], v245 offset:16384
	ds_read_b128 v[166:169], v245 offset:17408
	ds_read_b128 v[170:173], v245 offset:18432
	ds_read_b128 v[174:177], v245 offset:19456
	ds_read_b128 v[178:181], v245 offset:20480
	ds_read_b128 v[182:185], v245 offset:21504
	ds_read_b128 v[186:189], v245 offset:22528
	ds_read_b128 v[190:193], v245 offset:23552
	s_mov_b32 m0, s68
	s_nop 0
	global_load_lds_dwordx4 v241, s[6:7]
	s_mov_b32 m0, s69
	s_nop 0
	global_load_lds_dwordx4 v243, s[6:7]
	s_add_u32 s58, s6, 0x80000
	s_addc_u32 s59, s7, 0
	s_mov_b32 m0, s70
	s_nop 0
	global_load_lds_dwordx4 v241, s[58:59]
	s_mov_b32 m0, s71
	s_nop 0
	global_load_lds_dwordx4 v243, s[58:59]
	s_mov_b32 m0, s57
	s_nop 0
	global_load_lds_dwordx4 v240, s[8:9]
	s_mov_b32 m0, s72
	s_nop 0
	global_load_lds_dwordx4 v242, s[8:9]
	s_waitcnt vmcnt(8)
	s_waitcnt lgkmcnt(0)
	s_barrier
	s_setprio 1
	s_waitcnt lgkmcnt(7)
	v_mfma_f32_16x16x32_bf16 v[30:33], v[130:133], v[162:165], v[30:33]
	v_mfma_f32_16x16x32_bf16 v[26:29], v[138:141], v[162:165], v[26:29]
	s_waitcnt lgkmcnt(5)
	v_mfma_f32_16x16x32_bf16 v[22:25], v[130:133], v[170:173], v[22:25]
	v_mfma_f32_16x16x32_bf16 v[18:21], v[138:141], v[170:173], v[18:21]
	s_waitcnt lgkmcnt(3)
	v_mfma_f32_16x16x32_bf16 v[14:17], v[130:133], v[178:181], v[14:17]
	v_mfma_f32_16x16x32_bf16 v[10:13], v[138:141], v[178:181], v[10:13]
	s_waitcnt lgkmcnt(1)
	v_mfma_f32_16x16x32_bf16 v[6:9], v[130:133], v[186:189], v[6:9]
	v_mfma_f32_16x16x32_bf16 v[2:5], v[138:141], v[186:189], v[2:5]
	v_mfma_f32_16x16x32_bf16 v[30:33], v[134:137], v[166:169], v[30:33]
	v_mfma_f32_16x16x32_bf16 v[26:29], v[142:145], v[166:169], v[26:29]
	v_mfma_f32_16x16x32_bf16 v[22:25], v[134:137], v[174:177], v[22:25]
	v_mfma_f32_16x16x32_bf16 v[18:21], v[142:145], v[174:177], v[18:21]
	v_mfma_f32_16x16x32_bf16 v[14:17], v[134:137], v[182:185], v[14:17]
	v_mfma_f32_16x16x32_bf16 v[10:13], v[142:145], v[182:185], v[10:13]
	s_waitcnt lgkmcnt(0)
	v_mfma_f32_16x16x32_bf16 v[6:9], v[134:137], v[190:193], v[6:9]
	v_mfma_f32_16x16x32_bf16 v[2:5], v[142:145], v[190:193], v[2:5]
	s_setprio 0
	s_setprio 1
	v_mfma_f32_16x16x32_bf16 v[94:97], v[146:149], v[162:165], v[94:97]
	v_mfma_f32_16x16x32_bf16 v[90:93], v[154:157], v[162:165], v[90:93]
	v_mfma_f32_16x16x32_bf16 v[86:89], v[146:149], v[170:173], v[86:89]
	v_mfma_f32_16x16x32_bf16 v[82:85], v[154:157], v[170:173], v[82:85]
	v_mfma_f32_16x16x32_bf16 v[78:81], v[146:149], v[178:181], v[78:81]
	v_mfma_f32_16x16x32_bf16 v[74:77], v[154:157], v[178:181], v[74:77]
	v_mfma_f32_16x16x32_bf16 v[70:73], v[146:149], v[186:189], v[70:73]
	v_mfma_f32_16x16x32_bf16 v[34:37], v[154:157], v[186:189], v[34:37]
	v_mfma_f32_16x16x32_bf16 v[94:97], v[150:153], v[166:169], v[94:97]
	v_mfma_f32_16x16x32_bf16 v[90:93], v[158:161], v[166:169], v[90:93]
	v_mfma_f32_16x16x32_bf16 v[86:89], v[150:153], v[174:177], v[86:89]
	v_mfma_f32_16x16x32_bf16 v[82:85], v[158:161], v[174:177], v[82:85]
	v_mfma_f32_16x16x32_bf16 v[78:81], v[150:153], v[182:185], v[78:81]
	v_mfma_f32_16x16x32_bf16 v[74:77], v[158:161], v[182:185], v[74:77]
	v_mfma_f32_16x16x32_bf16 v[70:73], v[150:153], v[190:193], v[70:73]
	v_mfma_f32_16x16x32_bf16 v[34:37], v[158:161], v[190:193], v[34:37]
	s_setprio 0
	s_barrier
; #define PG8_LDA(dst, b, h) do { _Pragma("unroll") for (int m = 0; m < 4; ++m) _Pragma("unroll") for (int k = 0; k < 2; ++k) dst[m][k] = *(const LAS bf16x8*)(lds + PG8_SA(b, h) + aoff + m * 2048 + k * 1024); } while (0)
; #define PG8_LDB(dst, b, h) do { _Pragma("unroll") for (int n = 0; n < 2; ++n) _Pragma("unroll") for (int k = 0; k < 2; ++k) dst[n][k] = *(const LAS bf16x8*)(lds + PG8_SB(b, h) + boff + n * 2048 + k * 1024); } while (0)
; #define PG8_MMA(ai, bj, At, Bt) do { __builtin_amdgcn_s_setprio(1); _Pragma("unroll") for (int m = 0; m < 4; ++m) _Pragma("unroll") for (int n = 0; n < 2; ++n) _Pragma("unroll") for (int k = 0; k < 2; ++k) \
;         acc[ai][bj][m][n] = __builtin_amdgcn_mfma_f32_16x16x32_bf16(Bt[n][k], At[m][k], acc[ai][bj][m][n], 0, 0, 0); __builtin_amdgcn_s_setprio(0); } while (0)
; #define PG8_WAIT_V(n) asm volatile("s_waitcnt vmcnt(" #n ")" ::: "memory")
; #define PG8_WAIT_L(n) asm volatile("s_waitcnt lgkmcnt(" #n ")" ::: "memory")
; #define PG8_BAR __builtin_amdgcn_s_barrier()
; #define PG8_SCHED __builtin_amdgcn_sched_barrier(0)
;     ...
;             PG8_LDB(B0, 1, 0); PG8_LDB(B1, 1, 1); PG8_SCHED; PG8_LDA(At, 1, 0); PG8_STAGE(PG8_SA(0, 1), a2 + hstepA, voffA);
;             PG8_WAIT_V(8); PG8_WAIT_L(0); PG8_BAR; PG8_MMA(0, 0, At, B0); PG8_MMA(0, 1, At, B1); PG8_BAR; PG8_SCHED;
;             PG8_LDA(At, 1, 1); PG8_STAGE(PG8_SB(1, 0), b3, voffB); PG8_STAGE(PG8_SB(1, 1), b3 + hstepB, voffB); PG8_STAGE(PG8_SA(1, 0), a3, voffA);
;             PG8_WAIT_V(8); PG8_WAIT_L(0); PG8_BAR; PG8_MMA(1, 0, At, B0); PG8_MMA(1, 1, At, B1); PG8_BAR; PG8_SCHED;
;         }
;         if (wr == 0) PG8_BAR;
	v_add_u32_e32 v0, 0x18000, v244
	ds_read_b128 v[130:133], v0
	ds_read_b128 v[134:137], v0 offset:1024
	ds_read_b128 v[138:141], v0 offset:2048
	ds_read_b128 v[142:145], v0 offset:3072
	v_add_u32_e32 v0, 0x1c000, v244
	ds_read_b128 v[146:149], v0
	ds_read_b128 v[150:153], v0 offset:1024
	ds_read_b128 v[154:157], v0 offset:2048
	ds_read_b128 v[158:161], v0 offset:3072
	ds_read_b128 v[162:165], v245 offset:32768
	ds_read_b128 v[166:169], v245 offset:33792
	ds_read_b128 v[170:173], v245 offset:34816
	ds_read_b128 v[174:177], v245 offset:35840
	ds_read_b128 v[178:181], v245 offset:36864
	ds_read_b128 v[182:185], v245 offset:37888
	ds_read_b128 v[186:189], v245 offset:38912
	ds_read_b128 v[190:193], v245 offset:39936
	s_add_u32 s8, s8, 0x80000
	s_addc_u32 s9, s9, 0
	s_mov_b32 m0, s73
	s_nop 0
	global_load_lds_dwordx4 v240, s[8:9]
	s_mov_b32 m0, s76
	s_nop 0
	global_load_lds_dwordx4 v242, s[8:9]
	s_waitcnt vmcnt(8)
	s_waitcnt lgkmcnt(0)
	s_barrier
	s_setprio 1
	s_waitcnt lgkmcnt(7)
	v_mfma_f32_16x16x32_bf16 v[66:69], v[130:133], v[162:165], v[66:69]
	v_mfma_f32_16x16x32_bf16 v[62:65], v[138:141], v[162:165], v[62:65]
	s_waitcnt lgkmcnt(5)
	v_mfma_f32_16x16x32_bf16 v[58:61], v[130:133], v[170:173], v[58:61]
	v_mfma_f32_16x16x32_bf16 v[54:57], v[138:141], v[170:173], v[54:57]
	s_waitcnt lgkmcnt(3)
	v_mfma_f32_16x16x32_bf16 v[50:53], v[130:133], v[178:181], v[50:53]
	v_mfma_f32_16x16x32_bf16 v[46:49], v[138:141], v[178:181], v[46:49]
	s_waitcnt lgkmcnt(1)
	v_mfma_f32_16x16x32_bf16 v[42:45], v[130:133], v[186:189], v[42:45]
	v_mfma_f32_16x16x32_bf16 v[38:41], v[138:141], v[186:189], v[38:41]
	v_mfma_f32_16x16x32_bf16 v[66:69], v[134:137], v[166:169], v[66:69]
	v_mfma_f32_16x16x32_bf16 v[62:65], v[142:145], v[166:169], v[62:65]
	v_mfma_f32_16x16x32_bf16 v[58:61], v[134:137], v[174:177], v[58:61]
	v_mfma_f32_16x16x32_bf16 v[54:57], v[142:145], v[174:177], v[54:57]
	v_mfma_f32_16x16x32_bf16 v[50:53], v[134:137], v[182:185], v[50:53]
	v_mfma_f32_16x16x32_bf16 v[46:49], v[142:145], v[182:185], v[46:49]
	s_waitcnt lgkmcnt(0)
	v_mfma_f32_16x16x32_bf16 v[42:45], v[134:137], v[190:193], v[42:45]
	v_mfma_f32_16x16x32_bf16 v[38:41], v[142:145], v[190:193], v[38:41]
	s_setprio 0
	s_setprio 1
	v_mfma_f32_16x16x32_bf16 v[126:129], v[146:149], v[162:165], v[126:129]
	v_mfma_f32_16x16x32_bf16 v[122:125], v[154:157], v[162:165], v[122:125]
	v_mfma_f32_16x16x32_bf16 v[118:121], v[146:149], v[170:173], v[118:121]
	v_mfma_f32_16x16x32_bf16 v[114:117], v[154:157], v[170:173], v[114:117]
	v_mfma_f32_16x16x32_bf16 v[110:113], v[146:149], v[178:181], v[110:113]
	v_mfma_f32_16x16x32_bf16 v[106:109], v[154:157], v[178:181], v[106:109]
	v_mfma_f32_16x16x32_bf16 v[102:105], v[146:149], v[186:189], v[102:105]
	v_mfma_f32_16x16x32_bf16 v[98:101], v[154:157], v[186:189], v[98:101]
	v_mfma_f32_16x16x32_bf16 v[126:129], v[150:153], v[166:169], v[126:129]
	v_mfma_f32_16x16x32_bf16 v[122:125], v[158:161], v[166:169], v[122:125]
	v_mfma_f32_16x16x32_bf16 v[118:121], v[150:153], v[174:177], v[118:121]
	v_mfma_f32_16x16x32_bf16 v[114:117], v[158:161], v[174:177], v[114:117]
	v_mfma_f32_16x16x32_bf16 v[110:113], v[150:153], v[182:185], v[110:113]
	v_mfma_f32_16x16x32_bf16 v[106:109], v[158:161], v[182:185], v[106:109]
	v_mfma_f32_16x16x32_bf16 v[102:105], v[150:153], v[190:193], v[102:105]
	v_mfma_f32_16x16x32_bf16 v[98:101], v[158:161], v[190:193], v[98:101]
	s_setprio 0
	s_barrier
	ds_read_b128 v[162:165], v245 offset:49152
	ds_read_b128 v[166:169], v245 offset:50176
	ds_read_b128 v[170:173], v245 offset:51200
	ds_read_b128 v[174:177], v245 offset:52224
	ds_read_b128 v[178:181], v245 offset:53248
	ds_read_b128 v[182:185], v245 offset:54272
	ds_read_b128 v[186:189], v245 offset:55296
	ds_read_b128 v[190:193], v245 offset:56320
	s_add_u32 s8, s6, 0x80
	s_addc_u32 s9, s7, 0
	s_mov_b32 m0, s80
	s_nop 0
	global_load_lds_dwordx4 v241, s[8:9]
	s_mov_b32 m0, s81
	s_nop 0
	global_load_lds_dwordx4 v243, s[8:9]
	s_add_u32 s6, s6, 0x80080
	s_addc_u32 s7, s7, 0
	s_mov_b32 m0, s84
	s_nop 0
	global_load_lds_dwordx4 v241, s[6:7]
	s_mov_b32 m0, s85
	s_nop 0
	global_load_lds_dwordx4 v243, s[6:7]
	s_mov_b32 m0, s82
	s_nop 0
	global_load_lds_dwordx4 v240, s[4:5]
	s_mov_b32 m0, s83
	s_nop 0
	global_load_lds_dwordx4 v242, s[4:5]
	s_waitcnt vmcnt(8)
	s_waitcnt lgkmcnt(0)
	s_barrier
	s_setprio 1
	s_waitcnt lgkmcnt(7)
	v_mfma_f32_16x16x32_bf16 v[30:33], v[130:133], v[162:165], v[30:33]
	v_mfma_f32_16x16x32_bf16 v[26:29], v[138:141], v[162:165], v[26:29]
	s_waitcnt lgkmcnt(5)
	v_mfma_f32_16x16x32_bf16 v[22:25], v[130:133], v[170:173], v[22:25]
	v_mfma_f32_16x16x32_bf16 v[18:21], v[138:141], v[170:173], v[18:21]
	s_waitcnt lgkmcnt(3)
	v_mfma_f32_16x16x32_bf16 v[14:17], v[130:133], v[178:181], v[14:17]
	v_mfma_f32_16x16x32_bf16 v[10:13], v[138:141], v[178:181], v[10:13]
	s_waitcnt lgkmcnt(1)
	v_mfma_f32_16x16x32_bf16 v[6:9], v[130:133], v[186:189], v[6:9]
	v_mfma_f32_16x16x32_bf16 v[2:5], v[138:141], v[186:189], v[2:5]
	v_mfma_f32_16x16x32_bf16 v[30:33], v[134:137], v[166:169], v[30:33]
	v_mfma_f32_16x16x32_bf16 v[26:29], v[142:145], v[166:169], v[26:29]
	v_mfma_f32_16x16x32_bf16 v[22:25], v[134:137], v[174:177], v[22:25]
	v_mfma_f32_16x16x32_bf16 v[18:21], v[142:145], v[174:177], v[18:21]
	v_mfma_f32_16x16x32_bf16 v[14:17], v[134:137], v[182:185], v[14:17]
	v_mfma_f32_16x16x32_bf16 v[10:13], v[142:145], v[182:185], v[10:13]
	s_waitcnt lgkmcnt(0)
	v_mfma_f32_16x16x32_bf16 v[6:9], v[134:137], v[190:193], v[6:9]
	v_mfma_f32_16x16x32_bf16 v[2:5], v[142:145], v[190:193], v[2:5]
	s_setprio 0
	s_setprio 1
	v_mfma_f32_16x16x32_bf16 v[94:97], v[146:149], v[162:165], v[94:97]
	v_mfma_f32_16x16x32_bf16 v[90:93], v[154:157], v[162:165], v[90:93]
	v_mfma_f32_16x16x32_bf16 v[86:89], v[146:149], v[170:173], v[86:89]
	v_mfma_f32_16x16x32_bf16 v[82:85], v[154:157], v[170:173], v[82:85]
	v_mfma_f32_16x16x32_bf16 v[78:81], v[146:149], v[178:181], v[78:81]
	v_mfma_f32_16x16x32_bf16 v[74:77], v[154:157], v[178:181], v[74:77]
	v_mfma_f32_16x16x32_bf16 v[70:73], v[146:149], v[186:189], v[70:73]
	v_mfma_f32_16x16x32_bf16 v[34:37], v[154:157], v[186:189], v[34:37]
	v_mfma_f32_16x16x32_bf16 v[94:97], v[150:153], v[166:169], v[94:97]
	v_mfma_f32_16x16x32_bf16 v[90:93], v[158:161], v[166:169], v[90:93]
	v_mfma_f32_16x16x32_bf16 v[86:89], v[150:153], v[174:177], v[86:89]
	v_mfma_f32_16x16x32_bf16 v[82:85], v[158:161], v[174:177], v[82:85]
	v_mfma_f32_16x16x32_bf16 v[78:81], v[150:153], v[182:185], v[78:81]
	v_mfma_f32_16x16x32_bf16 v[74:77], v[158:161], v[182:185], v[74:77]
	v_mfma_f32_16x16x32_bf16 v[70:73], v[150:153], v[190:193], v[70:73]
	v_mfma_f32_16x16x32_bf16 v[34:37], v[158:161], v[190:193], v[34:37]
	s_setprio 0
	s_barrier
	s_add_u32 s11, s11, 0x100
	s_addc_u32 s13, s13, 0
	s_add_u32 s2, s2, 0x100
	s_addc_u32 s3, s3, 0
	s_cmp_ge_i32 s43, s12
	s_mov_b32 s4, s43
	s_cbranch_scc0 .LBB0_604
	s_and_b64 vcc, exec, s[36:37]
	s_cbranch_vccz .LBB0_607
	s_barrier
;     __device__ __forceinline__ void operator()(const f32x4 (&acc)[2][2][4][2], const pg8::Unit& u, int wr, int wc, int, int) const { const int ln_ = lane_now(); const int fr = ln_ & 15, fq = ln_ >> 4;
;         const int pp = u.pm % PPB; const int row0 = u.pm * 256 + wr * 64 + fr;
;         const int pn = u.pn;
;         if (pn == 52) {
;             if (wc == 0) {
; #pragma unroll
;                 for (int ai = 0; ai < 2; ++ai)
; #pragma unroll
;                     for (int m = 0; m < 4; ++m)
; #pragma unroll
;                         for (int n = 0; n < 2; ++n) *(f32x4*)(DT + (size_t)(row0 + ai * 128 + m * 16) * 32 + 8 * fq + 4 * n) = acc[ai][0][m][n];
;             }
;             return;
;         }
;         if (pn >= 28) {
;             const int jg = (pn - 28) >> 3, pnd = (pn - 28) & 7;
;             unsigned char* gq = (unsigned char*)P - WS_PROJ + gq_off(jg) + ((size_t)((u.pm * 8 + pnd) * 512 + (wr * 4 + wc) * 64 + ln_)) * 128;
; #pragma unroll
;             for (int ai = 0; ai < 2; ++ai)
; #pragma unroll
;                 for (int m = 0; m < 4; ++m) { u32x4 w;
; #pragma unroll
;                     for (int bj = 0; bj < 2; ++bj)
; #pragma unroll
;                         for (int n = 0; n < 2; ++n) { const f32x4 v = acc[ai][bj][m][n]; unsigned q = 0;
; #pragma unroll
;                             for (int e = 0; e < 4; ++e) { const float ex = __builtin_amdgcn_exp2f(v[e]);
;                                 q = __builtin_amdgcn_cvt_pk_u8_f32(fmaxf(__builtin_amdgcn_rcpf(__builtin_fmaf(ex, 1.0f / 255.0f, 1.0f / 255.0f)), 1.0f), e, q); }
;                             w[bj * 2 + n] = q; }
;                     *(u32x4*)(gq + (ai * 4 + m) * 16) = w; }
;             return;
;         }
;         if (pn >= 4 && pn < 8) {
;             float kmx0 = 0.f, kmx1 = 0.f;
; #pragma unroll
;             for (int ai = 0; ai < 2; ++ai)
; #pragma unroll
;                 for (int m = 0; m < 4; ++m) { const f32x4 a2 = acc[ai][0][m][0] * acc[ai][0][m][0] + acc[ai][0][m][1] * acc[ai][0][m][1], b2 = acc[ai][1][m][0] * acc[ai][1][m][0] + acc[ai][1][m][1] * acc[ai][1][m][1];
;                     kmx0 = fmaxf(kmx0, (a2[0] + a2[1]) + (a2[2] + a2[3])); kmx1 = fmaxf(kmx1, (b2[0] + b2[1]) + (b2[2] + b2[3])); }
; #pragma unroll
;             for (int o = 1; o < 16; o <<= 1) { kmx0 = fmaxf(kmx0, shx(kmx0, o, ln_)); kmx1 = fmaxf(kmx1, shx(kmx1, o, ln_)); }
.LBB0_607:
	s_lshl_b32 s2, s54, 8
	v_mbcnt_lo_u32_b32 v247, -1, 0
	v_mbcnt_hi_u32_b32 v247, -1, v247
	s_add_i32 s2, s2, s78
	v_and_b32_e32 v250, 15, v247
	v_ashrrev_i32_e32 v246, 4, v247
	v_or_b32_e32 v178, s2, v250
	s_cmp_lg_u32 s56, 52
	s_mov_b64 s[2:3], -1
	s_mov_b32 s59, 0x2dc00000
	s_mov_b32 s58, 0xbfc90fda
	s_cbranch_scc0 .LBB0_850
	s_cmp_lt_i32 s56, 28
	s_cbranch_scc0 .LBB0_847
	s_mul_hi_i32 s2, s54, 0x78787879
	s_lshr_b32 s3, s2, 31
	s_ashr_i32 s6, s2, 3
	s_add_i32 s6, s6, s3
	s_and_b32 s2, s56, -4
	s_cmp_lg_u32 s2, 4
	s_cbranch_scc1 .LBB0_613
	v_pk_mul_f32 v[130:131], v[68:69], v[68:69]
	v_pk_mul_f32 v[132:133], v[66:67], v[66:67]
	v_pk_fma_f32 v[130:131], v[64:65], v[64:65], v[130:131]
	v_pk_fma_f32 v[132:133], v[62:63], v[62:63], v[132:133]
	v_pk_mul_f32 v[134:135], v[128:129], v[128:129]
	v_pk_mul_f32 v[136:137], v[126:127], v[126:127]
	v_pk_fma_f32 v[134:135], v[124:125], v[124:125], v[134:135]
	v_pk_fma_f32 v[136:137], v[122:123], v[122:123], v[136:137]
	v_add_f32_e32 v0, v132, v133
	v_add_f32_e32 v130, v130, v131
	v_add_f32_e32 v0, v0, v130
	v_add_f32_e32 v130, v136, v137
	v_add_f32_e32 v131, v134, v135
	v_add_f32_e32 v138, v130, v131
	v_pk_mul_f32 v[130:131], v[60:61], v[60:61]
	v_pk_mul_f32 v[132:133], v[58:59], v[58:59]
	v_pk_fma_f32 v[130:131], v[56:57], v[56:57], v[130:131]
	v_pk_fma_f32 v[132:133], v[54:55], v[54:55], v[132:133]
	v_pk_mul_f32 v[134:135], v[120:121], v[120:121]
	v_pk_mul_f32 v[136:137], v[118:119], v[118:119]
	v_add_f32_e32 v132, v132, v133
	v_add_f32_e32 v130, v130, v131
	v_pk_fma_f32 v[134:135], v[116:117], v[116:117], v[134:135]
	v_pk_fma_f32 v[136:137], v[114:115], v[114:115], v[136:137]
	v_add_f32_e32 v130, v132, v130
	v_max3_f32 v0, v0, 0, v130
	v_add_f32_e32 v130, v136, v137
	v_add_f32_e32 v131, v134, v135
	v_add_f32_e32 v130, v130, v131
	v_max3_f32 v138, v138, 0, v130
	v_pk_mul_f32 v[130:131], v[52:53], v[52:53]
	v_pk_mul_f32 v[132:133], v[50:51], v[50:51]
	v_pk_fma_f32 v[130:131], v[48:49], v[48:49], v[130:131]
	v_pk_fma_f32 v[132:133], v[46:47], v[46:47], v[132:133]
	v_pk_mul_f32 v[134:135], v[112:113], v[112:113]
	v_pk_mul_f32 v[136:137], v[110:111], v[110:111]
	v_pk_fma_f32 v[134:135], v[108:109], v[108:109], v[134:135]
	v_pk_fma_f32 v[136:137], v[106:107], v[106:107], v[136:137]
	v_add_f32_e32 v132, v132, v133
	v_add_f32_e32 v130, v130, v131
	v_add_f32_e32 v139, v132, v130
	v_add_f32_e32 v130, v136, v137
	v_add_f32_e32 v131, v134, v135
	v_add_f32_e32 v140, v130, v131
	v_pk_mul_f32 v[130:131], v[44:45], v[44:45]
	v_pk_mul_f32 v[132:133], v[42:43], v[42:43]
	v_pk_fma_f32 v[130:131], v[40:41], v[40:41], v[130:131]
	v_pk_fma_f32 v[132:133], v[38:39], v[38:39], v[132:133]
	v_pk_mul_f32 v[134:135], v[104:105], v[104:105]
	v_pk_mul_f32 v[136:137], v[102:103], v[102:103]
	v_add_f32_e32 v132, v132, v133
	v_add_f32_e32 v130, v130, v131
	v_pk_fma_f32 v[134:135], v[100:101], v[100:101], v[134:135]
	v_pk_fma_f32 v[136:137], v[98:99], v[98:99], v[136:137]
	v_add_f32_e32 v130, v132, v130
	v_max3_f32 v0, v0, v139, v130
	v_add_f32_e32 v130, v136, v137
	v_add_f32_e32 v131, v134, v135
	v_add_f32_e32 v130, v130, v131
	v_max3_f32 v138, v138, v140, v130
	v_pk_mul_f32 v[130:131], v[32:33], v[32:33]
	v_pk_mul_f32 v[132:133], v[30:31], v[30:31]
	v_pk_fma_f32 v[130:131], v[28:29], v[28:29], v[130:131]
	v_pk_fma_f32 v[132:133], v[26:27], v[26:27], v[132:133]
	v_pk_mul_f32 v[134:135], v[96:97], v[96:97]
	v_pk_mul_f32 v[136:137], v[94:95], v[94:95]
	v_pk_fma_f32 v[134:135], v[92:93], v[92:93], v[134:135]
	v_pk_fma_f32 v[136:137], v[90:91], v[90:91], v[136:137]
	v_add_f32_e32 v132, v132, v133
	v_add_f32_e32 v130, v130, v131
	v_add_f32_e32 v139, v132, v130
	v_add_f32_e32 v130, v136, v137
	v_add_f32_e32 v131, v134, v135
	v_add_f32_e32 v140, v130, v131
	v_pk_mul_f32 v[130:131], v[24:25], v[24:25]
	v_pk_mul_f32 v[132:133], v[22:23], v[22:23]
	v_pk_fma_f32 v[130:131], v[20:21], v[20:21], v[130:131]
	v_pk_fma_f32 v[132:133], v[18:19], v[18:19], v[132:133]
	v_pk_mul_f32 v[134:135], v[88:89], v[88:89]
	v_pk_mul_f32 v[136:137], v[86:87], v[86:87]
	v_add_f32_e32 v132, v132, v133
	v_add_f32_e32 v130, v130, v131
	v_pk_fma_f32 v[134:135], v[84:85], v[84:85], v[134:135]
	v_pk_fma_f32 v[136:137], v[82:83], v[82:83], v[136:137]
	v_add_f32_e32 v130, v132, v130
	v_max3_f32 v0, v0, v139, v130
	v_add_f32_e32 v130, v136, v137
	v_add_f32_e32 v131, v134, v135
	v_add_f32_e32 v130, v130, v131
	v_max3_f32 v138, v138, v140, v130
	v_pk_mul_f32 v[130:131], v[16:17], v[16:17]
	v_pk_mul_f32 v[132:133], v[14:15], v[14:15]
	v_pk_fma_f32 v[130:131], v[12:13], v[12:13], v[130:131]
	v_pk_fma_f32 v[132:133], v[10:11], v[10:11], v[132:133]
	v_pk_mul_f32 v[134:135], v[80:81], v[80:81]
	v_pk_mul_f32 v[136:137], v[78:79], v[78:79]
	v_pk_fma_f32 v[134:135], v[76:77], v[76:77], v[134:135]
	v_pk_fma_f32 v[136:137], v[74:75], v[74:75], v[136:137]
	v_add_f32_e32 v132, v132, v133
	v_add_f32_e32 v130, v130, v131
	v_add_f32_e32 v139, v132, v130
	v_add_f32_e32 v130, v136, v137
	v_add_f32_e32 v131, v134, v135
	v_add_f32_e32 v140, v130, v131
	v_pk_mul_f32 v[130:131], v[8:9], v[8:9]
	v_pk_mul_f32 v[132:133], v[6:7], v[6:7]
	v_pk_fma_f32 v[130:131], v[4:5], v[4:5], v[130:131]
	v_pk_fma_f32 v[132:133], v[2:3], v[2:3], v[132:133]
	v_pk_mul_f32 v[134:135], v[72:73], v[72:73]
	v_pk_mul_f32 v[136:137], v[70:71], v[70:71]
	v_add_f32_e32 v132, v132, v133
	v_add_f32_e32 v130, v130, v131
	v_pk_fma_f32 v[134:135], v[36:37], v[36:37], v[134:135]
	v_pk_fma_f32 v[136:137], v[34:35], v[34:35], v[136:137]
	v_add_f32_e32 v130, v132, v130
	v_max3_f32 v0, v0, v139, v130
	v_add_f32_e32 v130, v136, v137
	v_add_f32_e32 v131, v134, v135
	v_add_f32_e32 v130, v130, v131
	v_lshlrev_b32_e32 v131, 2, v247
	v_xor_b32_e32 v132, 4, v131
	v_max3_f32 v130, v138, v140, v130
	ds_bpermute_b32 v133, v132, v0
	ds_bpermute_b32 v132, v132, v130
	v_cmp_eq_u32_e32 vcc, 0, v250
	s_waitcnt lgkmcnt(1)
	v_max_f32_e32 v133, v133, v133
	s_waitcnt lgkmcnt(0)
	v_max_f32_e32 v132, v132, v132
	v_max_f32_e32 v0, v0, v133
	v_xor_b32_e32 v133, 8, v131
	v_max_f32_e32 v130, v130, v132
	ds_bpermute_b32 v134, v133, v0
	ds_bpermute_b32 v132, v133, v130
	s_waitcnt lgkmcnt(1)
	v_max_f32_e32 v133, v134, v134
	s_waitcnt lgkmcnt(0)
	v_max_f32_e32 v132, v132, v132
	v_max_f32_e32 v0, v0, v133
	v_xor_b32_e32 v133, 16, v131
	v_max_f32_e32 v130, v130, v132
	ds_bpermute_b32 v134, v133, v0
	ds_bpermute_b32 v132, v133, v130
	s_waitcnt lgkmcnt(1)
	v_max_f32_e32 v133, v134, v134
	s_waitcnt lgkmcnt(0)
	v_max_f32_e32 v132, v132, v132
	v_max_f32_e32 v0, v0, v133
	v_max_f32_e32 v130, v130, v132
	v_xor_b32_e32 v132, 32, v131
	ds_bpermute_b32 v131, v132, v0
	ds_bpermute_b32 v132, v132, v130
	s_and_saveexec_b64 s[2:3], vcc
	s_cbranch_execz .LBB0_612
;     __device__ __forceinline__ void operator()(const f32x4 (&acc)[2][2][4][2], const pg8::Unit& u, int wr, int wc, int, int) const { const int ln_ = lane_now(); const int fr = ln_ & 15, fq = ln_ >> 4;
;     ...
;             if (fr == 0) { const int b = u.pm / PPB; unsigned* km = KM + (((b * 8 + (pn - 4) * 2) * 2 + (wc >> 1)) * 8 + (wc & 1) * 4 + fq);
;                 __hip_atomic_fetch_max(km, __float_as_uint(kmx0), __ATOMIC_RELAXED, __HIP_MEMORY_SCOPE_AGENT); __hip_atomic_fetch_max(km + 16, __float_as_uint(kmx1), __ATOMIC_RELAXED, __HIP_MEMORY_SCOPE_AGENT); } }
	s_lshl_b32 s4, s56, 2
	s_lshl_b32 s5, s6, 4
	s_add_i32 s4, s4, s5
	v_readlane_b32 s5, v254, 52
	s_or_b32 s4, s4, s5
	s_lshl_b32 s4, s4, 3
	s_waitcnt lgkmcnt(0)
	v_max_f32_e32 v132, v132, v132
	v_max_f32_e32 v130, v130, v130
	s_or_b32 s4, s4, s88
	v_max_f32_e32 v132, v130, v132
	v_max_f32_e32 v130, v131, v131
	v_max_f32_e32 v0, v0, v0
	s_addk_i32 s4, 0xff80
	v_max_f32_e32 v0, v0, v130
	v_add_u32_e32 v130, s4, v246
	v_ashrrev_i32_e32 v131, 31, v130
	v_lshl_add_u64 v[130:131], v[130:131], 2, s[34:35]
	global_atomic_umax v[130:131], v0, off
	global_atomic_umax v[130:131], v132, off offset:64

; __device__ __forceinline__ unsigned xb_ld(unsigned* p)              { return __hip_atomic_load(p, __ATOMIC_RELAXED, __HIP_MEMORY_SCOPE_AGENT); }
; __device__ __forceinline__ unsigned xb_add(unsigned* p, unsigned v) { return __hip_atomic_fetch_add(p, v, __ATOMIC_RELAXED, __HIP_MEMORY_SCOPE_AGENT); }
; __device__ __forceinline__ void xcd_barrier_complete(unsigned* bar, unsigned x, unsigned& nloc, unsigned& nx) {
;     const unsigned G = gridDim.x * gridDim.y * gridDim.z;
;     unsigned sum, cnt, mine, sp = 0u;
;     for (;;) {
;         sum = 0u; cnt = 0u; mine = 0u;
; #pragma unroll
;         for (unsigned j = 0; j < 16; ++j) { const unsigned c = xb_ld(&bar[XB_XCNT(j)]); sum += c; cnt += (c > 0u) ? 1u : 0u; mine = (j == x) ? c : mine; }
;         if (sum == G) break;
;         __builtin_amdgcn_s_sleep(1);
;         if ((++sp & 255u) == 0u) { if (xb_ld(&bar[XB_TMO])) break; if (sp > XB_SPIN_CAP) { atomicAdd(&bar[XB_TMO], 1u); break; } }
;     }
;     nloc = mine > 0u ? mine : 1u; nx = cnt > 0u ? cnt : 1u;
; }
; __device__ __forceinline__ void xcd_barrier(const XcdBarrier& b, const int tid) {
;     asm volatile("s_waitcnt vmcnt(0)" ::: "memory");
;     __syncthreads();
;     if (tid == 0) {
;         unsigned* bar = b.bar;
;         __builtin_amdgcn_s_waitcnt(0);
;         unsigned nloc = b.st[0], nx = b.st[1];
;         if (nloc == 0u) { xcd_barrier_complete(bar, b.x, nloc, nx); b.st[0] = nloc; b.st[1] = nx; }
;         const unsigned old = xb_add(&bar[XB_XSUB(b.x)], 1u);
.LBB0_861:
	v_readlane_b32 s0, v253, 24
	s_add_i32 s20, s0, 1
	s_cmp_ge_i32 s20, s85
	s_cbranch_scc1 .LBB0_873
	s_getreg_b32 s2, hwreg(HW_REG_XCC_ID, 0, 4)
	v_mbcnt_lo_u32_b32 v0, -1, 0
	v_mbcnt_hi_u32_b32 v0, -1, v0
	s_waitcnt vmcnt(0)
	s_nop 0
	v_sub_u32_e32 v0, 0, v0
	v_cmp_eq_u32_e32 vcc, s83, v0
	s_barrier
	s_and_saveexec_b64 s[0:1], vcc
	s_mov_b32 s55, 0xf534ddc0
	s_cbranch_execz .LBB0_915
	v_readlane_b32 s3, v253, 40
	s_waitcnt vmcnt(0) expcnt(0) lgkmcnt(0)
	s_and_b32 s8, s2, 15
	v_mov_b32_e32 v0, s3
	ds_read_b32 v3, v0
	v_readlane_b32 s3, v253, 41
	s_waitcnt lgkmcnt(0)
	v_cmp_ne_u32_e32 vcc, 0, v3
	v_mov_b32_e32 v0, s3
	ds_read_b32 v2, v0
	s_cbranch_vccnz .LBB0_879
	v_readlane_b32 s4, v252, 0
	v_readlane_b32 s5, v252, 1
	s_load_dwordx2 s[2:3], s[4:5], 0x4
	s_mov_b32 s10, 1
	s_waitcnt lgkmcnt(0)
	s_mul_i32 s9, s2, s82
	s_mul_i32 s9, s9, s3
	s_branch .LBB0_866

; #define LAS __attribute__((address_space(3)))
; __device__ __forceinline__ float bflo(unsigned u) { return __uint_as_float(u << 16); }
; __device__ __forceinline__ float bfhi(unsigned u) { return __uint_as_float(u & 0xffff0000u); }
; __device__ __forceinline__ unsigned short bf16_1(float v) { return (unsigned short)(cvt_pk_bf16(v, 0.f) & 0xffffu); }
; __device__ __forceinline__ void ssd_chain_fast(const Args& A_, Frame& F, int l, int cid) {
;     ...
;         for (int i = 0; i < 4; ++i) { const int item = tid + 512 * i, row = item >> 4, seg = item & 15; *(LAS u32x4*)(Cs + row * LS + seg * 8) = pc[i]; *(LAS u32x4*)(Bs + row * LS + seg * 8) = pb[i]; }
;         { const int row = tid >> 2, seg = tid & 3; const float dtv = pdt; const u32x4 xv = px;
;             LAS bf16_t* xo = XdT + (seg * 8) * LS + row;
;             xo[0 * LS] = bf16_1(bflo(xv.x) * dtv); xo[1 * LS] = bf16_1(bfhi(xv.x) * dtv); xo[2 * LS] = bf16_1(bflo(xv.y) * dtv); xo[3 * LS] = bf16_1(bfhi(xv.y) * dtv);
;             xo[4 * LS] = bf16_1(bflo(xv.z) * dtv); xo[5 * LS] = bf16_1(bfhi(xv.z) * dtv); xo[6 * LS] = bf16_1(bflo(xv.w) * dtv); xo[7 * LS] = bf16_1(bfhi(xv.w) * dtv); }
;         if (w == 0) {
;             float v0 = pv0 * a, v1 = pv1 * a;
; #pragma unroll
;             for (int o = 1; o < 64; o <<= 1) { const float t0 = __int_as_float(__builtin_amdgcn_ds_bpermute((lane - o) << 2, __float_as_int(v0))), t1 = __int_as_float(__builtin_amdgcn_ds_bpermute((lane - o) << 2, __float_as_int(v1))); if (lane >= o) { v0 += t0; v1 += t1; } }
;             const float tot0 = __int_as_float(__builtin_amdgcn_ds_bpermute(63 << 2, __float_as_int(v0))); v1 += tot0;
;             const float cend = __int_as_float(__builtin_amdgcn_ds_bpermute(63 << 2, __float_as_int(v1)));
;             csL[rho0] = v0 * 1.4426950408889634f; csL[rho1] = v1 * 1.4426950408889634f; ecsL[rho0] = __builtin_amdgcn_exp2f(v0 * 1.4426950408889634f); ecsL[rho1] = __builtin_amdgcn_exp2f(v1 * 1.4426950408889634f);
;             ewL[rho0] = __builtin_amdgcn_exp2f((cend - v0) * 1.4426950408889634f); ewL[rho1] = __builtin_amdgcn_exp2f((cend - v1) * 1.4426950408889634f);
;             if (lane == 0) misc[0] = __builtin_amdgcn_exp2f(cend * 1.4426950408889634f);
;         }
.LBB0_1058:
	s_waitcnt vmcnt(0)
	v_lshlrev_b32_e32 v0, 16, v66
	v_mul_f32_e32 v0, v152, v0
	s_waitcnt lgkmcnt(0)
	s_barrier
	ds_write_b128 v134, v[34:37]
	ds_write_b128 v134, v[38:41] offset:34816
	ds_write_b128 v136, v[42:45]
	ds_write_b128 v136, v[46:49] offset:34816
	ds_write_b128 v138, v[50:53]
	ds_write_b128 v138, v[54:57] offset:34816
	ds_write_b128 v140, v[58:61]
	ds_write_b128 v140, v[62:65] offset:34816
	v_cvt_pk_bf16_f32 v0, v0, v1
	ds_write_b16 v151, v0
	v_and_b32_e32 v0, 0xffff0000, v66
	v_mul_f32_e32 v0, v152, v0
	v_cvt_pk_bf16_f32 v0, v0, v1
	ds_write_b16 v151, v0 offset:272
	v_lshlrev_b32_e32 v0, 16, v67
	v_mul_f32_e32 v0, v152, v0
	v_cvt_pk_bf16_f32 v0, v0, v1
	ds_write_b16 v151, v0 offset:544
	v_and_b32_e32 v0, 0xffff0000, v67
	v_mul_f32_e32 v0, v152, v0
	v_cvt_pk_bf16_f32 v0, v0, v1
	ds_write_b16 v151, v0 offset:816
	v_lshlrev_b32_e32 v0, 16, v68
	v_mul_f32_e32 v0, v152, v0
	v_cvt_pk_bf16_f32 v0, v0, v1
	ds_write_b16 v151, v0 offset:1088
	v_and_b32_e32 v0, 0xffff0000, v68
	v_mul_f32_e32 v0, v152, v0
	v_cvt_pk_bf16_f32 v0, v0, v1
	ds_write_b16 v151, v0 offset:1360
	v_lshlrev_b32_e32 v0, 16, v69
	v_mul_f32_e32 v0, v152, v0
	v_cvt_pk_bf16_f32 v0, v0, v1
	ds_write_b16 v151, v0 offset:1632
	v_and_b32_e32 v0, 0xffff0000, v69
	v_cndmask_b32_e64 v18, 0, 1, s[82:83]
	v_mul_f32_e32 v0, v152, v0
	v_cmp_ne_u32_e64 s[80:81], 1, v18
	s_andn2_b64 vcc, exec, s[82:83]
	v_cvt_pk_bf16_f32 v0, v0, v1
	ds_write_b16 v151, v0 offset:1904
	s_cbranch_vccnz .LBB0_1062
	v_mul_f32_e64 v0, v148, -v150
	v_mul_f32_e64 v18, v149, -v150
	s_nop 0
	s_nop 0
	v_add_f32_dpp v0, v0, v0 row_shr:1 row_mask:0xf bank_mask:0xf
	v_add_f32_dpp v18, v18, v18 row_shr:1 row_mask:0xf bank_mask:0xf
	s_nop 0
	v_add_f32_dpp v0, v0, v0 row_shr:2 row_mask:0xf bank_mask:0xf
	v_add_f32_dpp v18, v18, v18 row_shr:2 row_mask:0xf bank_mask:0xf
	s_nop 0
	v_add_f32_dpp v0, v0, v0 row_shr:4 row_mask:0xf bank_mask:0xf
	v_add_f32_dpp v18, v18, v18 row_shr:4 row_mask:0xf bank_mask:0xf
	s_nop 0
	v_add_f32_dpp v0, v0, v0 row_shr:8 row_mask:0xf bank_mask:0xf
	v_add_f32_dpp v18, v18, v18 row_shr:8 row_mask:0xf bank_mask:0xf
	s_nop 0
	v_add_f32_dpp v0, v0, v0 row_bcast:15 row_mask:0xa bank_mask:0xf
	v_add_f32_dpp v18, v18, v18 row_bcast:15 row_mask:0xa bank_mask:0xf
	s_nop 0
	v_add_f32_dpp v0, v0, v0 row_bcast:31 row_mask:0xc bank_mask:0xf
	v_add_f32_dpp v18, v18, v18 row_bcast:31 row_mask:0xc bank_mask:0xf
	s_nop 1
	v_readlane_b32 s18, v0, 63
	v_mul_f32_e32 v19, 0x3fb8aa3b, v0
	ds_write_b32 v153, v19
	v_add_f32_e32 v18, s18, v18
	v_exp_f32_e32 v19, v19
	v_readlane_b32 s27, v18, 63
	v_mul_f32_e32 v20, 0x3fb8aa3b, v18
	ds_write_b32 v154, v20
	v_sub_f32_e32 v0, s27, v0
	v_exp_f32_e32 v20, v20
	v_mul_f32_e32 v0, 0x3fb8aa3b, v0
	v_sub_f32_e32 v18, s27, v18
	v_exp_f32_e32 v0, v0
	v_mul_f32_e32 v18, 0x3fb8aa3b, v18
	v_exp_f32_e32 v18, v18
	ds_write_b32 v155, v19
	ds_write_b32 v156, v20
	ds_write_b32 v157, v0
	ds_write_b32 v158, v18
	s_and_saveexec_b64 s[18:19], s[0:1]
	s_cbranch_execz .LBB0_1061
	v_mov_b32_e32 v0, 0x3fb8aa3b
	v_mul_f32_e32 v0, s27, v0
	v_exp_f32_e32 v0, v0
	v_readlane_b32 s27, v253, 49
	s_nop 1
	v_mov_b32_e32 v18, s27
	ds_write_b32 v18, v0

; template <bool FIRST = false>
; __device__ __forceinline__ void partialSM(f32x16& p0, f32x16& p1, float& m_reg, float& mn, float& alpha, const bool nomax) {
;   if (nomax) { mn = 0.f; alpha = 1.f;
; #pragma unroll
;     for (int r = 0; r < 16; ++r) p0[r] = __builtin_amdgcn_exp2f(p0[r]);
;     return; }
;   float pmax = p0[0];
; #pragma unroll
;   for (int r = 1; r < 16; ++r) pmax = fmaxf(pmax, p0[r]);
; #pragma unroll
;   for (int r = 0; r < 16; ++r) pmax = fmaxf(pmax, p1[r]);
;   { auto rr = __builtin_amdgcn_permlane32_swap(__float_as_uint(pmax), __float_as_uint(pmax), false, false); pmax = fmaxf(__uint_as_float(rr[0]), __uint_as_float(rr[1])); }
;   if (FIRST) { m_reg = (__builtin_fabsf(pmax) <= THRL) ? 0.f : pmax; mn = m_reg; alpha = 1.f; }
;   else if (__builtin_expect(__all(pmax - m_reg <= THRL), 1)) { mn = m_reg; alpha = 1.f; }
;   else { mn = fmaxf(m_reg, pmax); alpha = __builtin_amdgcn_exp2f(m_reg - mn); m_reg = mn; }
;   if (__builtin_expect(__any(mn != 0.f), 0)) {
; #pragma unroll
;     for (int r = 0; r < 16; ++r) { p0[r] = p0[r] - mn; p1[r] = p1[r] - mn; } }
; #pragma unroll
;   for (int r = 0; r < 16; ++r) p0[r] = __builtin_amdgcn_exp2f(p0[r]);
; }
; __device__ __forceinline__ void finishSM(f32x16& p0, f32x16& p1, float alpha, float& l_reg, bf16x8& pa0, bf16x8& pa1, bf16x8& pa2, bf16x8& pa3) {
; #pragma unroll
;   for (int r = 0; r < 16; ++r) p1[r] = __builtin_amdgcn_exp2f(p1[r]);
;   typedef float f32x8_ __attribute__((ext_vector_type(8))); typedef float f32x2_ __attribute__((ext_vector_type(2)));
;   const f32x16 s16_ = p0 + p1; const f32x8_ s8_ = s16_.lo + s16_.hi; const f32x4 s4_ = s8_.lo + s8_.hi; const f32x2_ s2_ = s4_.lo + s4_.hi;
;   float ps = s2_.x + s2_.y;
;   { auto rr = __builtin_amdgcn_permlane32_swap(__float_as_uint(ps), __float_as_uint(ps), false, false); ps = __uint_as_float(rr[0]) + __uint_as_float(rr[1]); }
;   l_reg = l_reg * alpha + ps;
;     ...
;   A128_PK4(p0, 0, pa0); A128_PK4(p0, 8, pa1); A128_PK4(p1, 0, pa2); A128_PK4(p1, 8, pa3);
;     ...
; }
; __device__ __forceinline__ void qkt(f32x16& p0, f32x16& p1, const char* Ks, const bf16x8* qr, int r32, int hi) {
; #pragma unroll
;   for (int i = 0; i < 16; ++i) { p0[i] = 0.f; p1[i] = 0.f; }
; #pragma unroll
;   for (int d0 = 0; d0 < 4; ++d0) { const int cb = (d0 * 16 + hi * 8) * 2;
;     const bf16x8 b0 = *reinterpret_cast<const bf16x8*>(Ks + A128_KSWZ(r32, cb));
.LBB0_1110:
	ds_read_b128 v[2:5], v204 offset:40960
	ds_read_b128 v[6:9], v204 offset:45056
	ds_read_b128 v[232:235], v205 offset:40960
	ds_read_b128 v[236:239], v205 offset:45056
	ds_read_b128 v[240:243], v192 offset:40960
	ds_read_b128 v[244:247], v192 offset:45056
	v_exp_f32_e32 v10, v88
	v_exp_f32_e32 v11, v89
	v_exp_f32_e32 v12, v90
	s_waitcnt lgkmcnt(5)
	v_mfma_f32_32x32x16_bf16 v[112:127], v[2:5], v[140:143], 0
	v_exp_f32_e32 v13, v91
	v_exp_f32_e32 v194, v92
	v_exp_f32_e32 v195, v93
	v_exp_f32_e32 v196, v94
	v_exp_f32_e32 v197, v95
	v_pk_add_f32 v[14:15], v[168:169], v[12:13]
	v_pk_add_f32 v[90:91], v[164:165], v[194:195]
	s_waitcnt lgkmcnt(4)
	v_mfma_f32_32x32x16_bf16 v[96:111], v[6:9], v[140:143], 0
	ds_read_b128 v[2:5], v193 offset:40960
	ds_read_b128 v[6:9], v193 offset:45056
	s_waitcnt lgkmcnt(5)
	v_mfma_f32_32x32x16_bf16 v[112:127], v[232:235], v[136:139], v[112:127]
	s_waitcnt lgkmcnt(4)
	v_mfma_f32_32x32x16_bf16 v[96:111], v[236:239], v[136:139], v[96:111]
	s_waitcnt lgkmcnt(3)
	v_mfma_f32_32x32x16_bf16 v[112:127], v[240:243], v[132:135], v[112:127]
	s_waitcnt lgkmcnt(2)
	v_mfma_f32_32x32x16_bf16 v[96:111], v[244:247], v[132:135], v[96:111]
	s_waitcnt lgkmcnt(1)
	v_mfma_f32_32x32x16_bf16 v[112:127], v[2:5], v[128:131], v[112:127]
	v_exp_f32_e32 v2, v80
	v_exp_f32_e32 v3, v81
	v_exp_f32_e32 v4, v82
	v_exp_f32_e32 v5, v83
	v_pk_add_f32 v[82:83], v[162:163], v[196:197]
	v_pk_add_f32 v[88:89], v[178:179], v[2:3]
	v_pk_add_f32 v[80:81], v[176:177], v[4:5]
	s_waitcnt lgkmcnt(0)
	v_mfma_f32_32x32x16_bf16 v[96:111], v[6:9], v[128:131], v[96:111]
	v_exp_f32_e32 v6, v84
	v_exp_f32_e32 v7, v85
	v_exp_f32_e32 v8, v86
	v_exp_f32_e32 v9, v87
	v_pk_add_f32 v[86:87], v[170:171], v[10:11]
	v_pk_add_f32 v[92:93], v[174:175], v[6:7]
	v_pk_add_f32 v[86:87], v[88:89], v[86:87]
	v_pk_add_f32 v[84:85], v[172:173], v[8:9]
	v_pk_add_f32 v[90:91], v[92:93], v[90:91]
	v_pk_add_f32 v[82:83], v[84:85], v[82:83]
	v_pk_add_f32 v[14:15], v[80:81], v[14:15]
	v_pk_add_f32 v[80:81], v[86:87], v[90:91]
	v_pk_add_f32 v[14:15], v[14:15], v[82:83]
	s_nop 0
	v_pk_add_f32 v[14:15], v[80:81], v[14:15]
	v_cvt_pk_bf16_f32 v80, v178, v179
	v_cvt_pk_bf16_f32 v81, v176, v177
	v_cvt_pk_bf16_f32 v82, v174, v175
	v_cvt_pk_bf16_f32 v83, v172, v173
	v_cvt_pk_bf16_f32 v84, v170, v171
	s_nop 0
	v_pk_add_f32 v[14:15], v[14:15], v[14:15] op_sel:[0,1] op_sel_hi:[1,0]
	v_cvt_pk_bf16_f32 v85, v168, v169
	v_cvt_pk_bf16_f32 v86, v164, v165
	v_cvt_pk_bf16_f32 v87, v162, v163
	v_cvt_pk_bf16_f32 v88, v2, v3
	v_cvt_pk_bf16_f32 v89, v4, v5
	s_nop 0
	v_mov_b32_e32 v0, v14
	s_nop 1
	v_permlane32_swap_b32_e32 v14, v0
	v_cvt_pk_bf16_f32 v90, v6, v7
	v_cvt_pk_bf16_f32 v91, v8, v9
	v_cvt_pk_bf16_f32 v92, v10, v11
	v_cvt_pk_bf16_f32 v93, v12, v13
	v_cvt_pk_bf16_f32 v94, v194, v195
	v_cvt_pk_bf16_f32 v95, v196, v197
	v_lshl_add_u64 v[162:163], v[160:161], 0, s[8:9]
	s_mov_b32 s2, 0xe2e1000
	v_add_co_u32_e32 v2, vcc, s2, v162
	s_mov_b32 s2, 0xe3b1000
	s_nop 0
	v_addc_co_u32_e32 v3, vcc, 0, v163, vcc
	v_add_co_u32_e32 v6, vcc, s2, v162
	v_lshl_add_u64 v[164:165], v[158:159], 0, s[8:9]
	s_nop 0
	v_addc_co_u32_e32 v7, vcc, 0, v163, vcc
	s_mov_b32 s2, 0xe2e0000
	v_add_co_u32_e32 v10, vcc, s2, v164
	global_load_dwordx4 v[2:5], v[2:3], off
	s_nop 0
	global_load_dwordx4 v[6:9], v[6:7], off
	v_addc_co_u32_e32 v11, vcc, 0, v165, vcc
	global_load_dwordx4 v[10:13], v[10:11], off offset:2048
	ds_read_b64_tr_b16 v[168:169], v190 offset:0
	ds_read_b64_tr_b16 v[170:171], v190 offset:0x800
	ds_read_b64_tr_b16 v[172:173], v190 offset:0x1000
	ds_read_b64_tr_b16 v[174:175], v190 offset:0x1800
	ds_read_b64_tr_b16 v[176:177], v190 offset:0x2000
	ds_read_b64_tr_b16 v[178:179], v190 offset:0x2800
	ds_read_b64_tr_b16 v[194:195], v190 offset:0x3000
	ds_read_b64_tr_b16 v[196:197], v190 offset:0x3800
	ds_read_b64_tr_b16 v[232:233], v190 offset:0x200
	ds_read_b64_tr_b16 v[234:235], v190 offset:0xa00
	ds_read_b64_tr_b16 v[236:237], v190 offset:0x1200
	ds_read_b64_tr_b16 v[238:239], v190 offset:0x1a00
	ds_read_b64_tr_b16 v[240:241], v190 offset:0x2200
	ds_read_b64_tr_b16 v[242:243], v190 offset:0x2a00
	ds_read_b64_tr_b16 v[244:245], v190 offset:0x3200
	ds_read_b64_tr_b16 v[246:247], v190 offset:0x3a00
	s_waitcnt lgkmcnt(8)
	s_nop 0
	v_mfma_f32_32x32x16_bf16 v[16:31], v[80:83], v[168:171], v[16:31]
	ds_read_b64_tr_b16 v[168:169], v190 offset:0x400
	ds_read_b64_tr_b16 v[170:171], v190 offset:0xc00
	v_mfma_f32_32x32x16_bf16 v[16:31], v[84:87], v[172:175], v[16:31]
	ds_read_b64_tr_b16 v[172:173], v190 offset:0x1400
	ds_read_b64_tr_b16 v[174:175], v190 offset:0x1c00
	v_mfma_f32_32x32x16_bf16 v[16:31], v[88:91], v[176:179], v[16:31]
	ds_read_b64_tr_b16 v[176:177], v190 offset:0x2400
	ds_read_b64_tr_b16 v[178:179], v190 offset:0x2c00
	v_mfma_f32_32x32x16_bf16 v[16:31], v[92:95], v[194:197], v[16:31]
	ds_read_b64_tr_b16 v[194:195], v190 offset:0x3400
	ds_read_b64_tr_b16 v[196:197], v190 offset:0x3c00
	s_waitcnt lgkmcnt(8)
	v_mfma_f32_32x32x16_bf16 v[32:47], v[80:83], v[232:235], v[32:47]
	ds_read_b64_tr_b16 v[232:233], v190 offset:0x600
	ds_read_b64_tr_b16 v[234:235], v190 offset:0xe00
	v_mfma_f32_32x32x16_bf16 v[32:47], v[84:87], v[236:239], v[32:47]
	ds_read_b64_tr_b16 v[236:237], v190 offset:0x1600
	ds_read_b64_tr_b16 v[238:239], v190 offset:0x1e00
	v_mfma_f32_32x32x16_bf16 v[32:47], v[88:91], v[240:243], v[32:47]
	ds_read_b64_tr_b16 v[240:241], v190 offset:0x2600
	ds_read_b64_tr_b16 v[242:243], v190 offset:0x2e00
	v_mfma_f32_32x32x16_bf16 v[32:47], v[92:95], v[244:247], v[32:47]
	ds_read_b64_tr_b16 v[244:245], v190 offset:0x3600
	ds_read_b64_tr_b16 v[246:247], v190 offset:0x3e00
	s_waitcnt lgkmcnt(8)
	v_mfma_f32_32x32x16_bf16 v[48:63], v[80:83], v[168:171], v[48:63]
	v_mfma_f32_32x32x16_bf16 v[48:63], v[84:87], v[172:175], v[48:63]
	v_mfma_f32_32x32x16_bf16 v[48:63], v[88:91], v[176:179], v[48:63]
	v_mfma_f32_32x32x16_bf16 v[48:63], v[92:95], v[194:197], v[48:63]
	s_waitcnt lgkmcnt(0)
	v_mfma_f32_32x32x16_bf16 v[64:79], v[80:83], v[232:235], v[64:79]
	v_cndmask_b32_e64 v15, 0, 1, s[18:19]
	v_cmp_ne_u32_e64 s[4:5], 1, v15
	s_andn2_b64 vcc, exec, s[18:19]
	v_mfma_f32_32x32x16_bf16 v[64:79], v[84:87], v[236:239], v[64:79]
	v_mfma_f32_32x32x16_bf16 v[64:79], v[88:91], v[240:243], v[64:79]
	v_mfma_f32_32x32x16_bf16 v[64:79], v[92:95], v[244:247], v[64:79]
	s_cbranch_vccnz .LBB0_1113
; template <bool FIRST = false>
; __device__ __forceinline__ void partialSM(f32x16& p0, f32x16& p1, float& m_reg, float& mn, float& alpha, const bool nomax) {
;     ...
;   float pmax = p0[0];
; #pragma unroll
;   for (int r = 1; r < 16; ++r) pmax = fmaxf(pmax, p0[r]);
; #pragma unroll
;   for (int r = 0; r < 16; ++r) pmax = fmaxf(pmax, p1[r]);
;   { auto rr = __builtin_amdgcn_permlane32_swap(__float_as_uint(pmax), __float_as_uint(pmax), false, false); pmax = fmaxf(__uint_as_float(rr[0]), __uint_as_float(rr[1])); }
;   if (FIRST) { m_reg = (__builtin_fabsf(pmax) <= THRL) ? 0.f : pmax; mn = m_reg; alpha = 1.f; }
;   else if (__builtin_expect(__all(pmax - m_reg <= THRL), 1)) { mn = m_reg; alpha = 1.f; }
;   else { mn = fmaxf(m_reg, pmax); alpha = __builtin_amdgcn_exp2f(m_reg - mn); m_reg = mn; }
;   if (__builtin_expect(__any(mn != 0.f), 0)) {
	v_max_f32_e32 v15, v113, v113
	v_max_f32_e32 v80, v112, v112
	v_max_f32_e32 v15, v80, v15
	v_max3_f32 v15, v15, v114, v115
	v_max3_f32 v15, v15, v116, v117
	v_max3_f32 v15, v15, v118, v119
	v_max3_f32 v15, v15, v120, v121
	v_max3_f32 v15, v15, v122, v123
	v_max3_f32 v15, v15, v124, v125
	v_max3_f32 v15, v15, v126, v127
	v_max3_f32 v15, v15, v96, v97
	v_max3_f32 v15, v15, v98, v99
	v_max3_f32 v15, v15, v100, v101
	v_max3_f32 v15, v15, v102, v103
	v_max3_f32 v15, v15, v104, v105
	v_max3_f32 v15, v15, v106, v107
	v_max3_f32 v15, v15, v108, v109
	v_max3_f32 v15, v15, v110, v111
	v_mov_b32_e32 v80, v15
	s_nop 1
	v_permlane32_swap_b32_e32 v15, v80
	v_max_f32_e32 v80, v80, v80
	v_max_f32_e32 v15, v15, v15
	v_max_f32_e32 v15, v15, v80
	v_sub_f32_e32 v80, v15, v167
	v_cmp_ge_f32_e32 vcc, s74, v80
	s_cmp_eq_u64 vcc, exec
	v_max_f32_e32 v80, v167, v167
	v_max_f32_e32 v15, v80, v15
	s_cselect_b64 s[6:7], -1, 0
	v_cndmask_b32_e64 v168, v15, v167, s[6:7]
	v_cmp_neq_f32_e32 vcc, 0, v168
	s_cbranch_vccnz .LBB0_1132

; #define A128_PK4(P, BASE, OUT) do { u32x4 w = {cvt_pk_bf16(P[BASE + 0], P[BASE + 1]), cvt_pk_bf16(P[BASE + 2], P[BASE + 3]), cvt_pk_bf16(P[BASE + 4], P[BASE + 5]), cvt_pk_bf16(P[BASE + 6], P[BASE + 7])}; \
;     OUT = __builtin_bit_cast(bf16x8, w); } while (0)
; template <bool FIRST = false>
; __device__ __forceinline__ void partialSM(f32x16& p0, f32x16& p1, float& m_reg, float& mn, float& alpha, const bool nomax) {
;     ...
;   for (int r = 0; r < 16; ++r) p0[r] = __builtin_amdgcn_exp2f(p0[r]);
; }
; __device__ __forceinline__ void finishSM(f32x16& p0, f32x16& p1, float alpha, float& l_reg, bf16x8& pa0, bf16x8& pa1, bf16x8& pa2, bf16x8& pa3) {
; #pragma unroll
;   for (int r = 0; r < 16; ++r) p1[r] = __builtin_amdgcn_exp2f(p1[r]);
;   typedef float f32x8_ __attribute__((ext_vector_type(8))); typedef float f32x2_ __attribute__((ext_vector_type(2)));
;   const f32x16 s16_ = p0 + p1; const f32x8_ s8_ = s16_.lo + s16_.hi; const f32x4 s4_ = s8_.lo + s8_.hi; const f32x2_ s2_ = s4_.lo + s4_.hi;
;   float ps = s2_.x + s2_.y;
;   { auto rr = __builtin_amdgcn_permlane32_swap(__float_as_uint(ps), __float_as_uint(ps), false, false); ps = __uint_as_float(rr[0]) + __uint_as_float(rr[1]); }
;   l_reg = l_reg * alpha + ps;
;     ...
;   A128_PK4(p0, 0, pa0); A128_PK4(p0, 8, pa1); A128_PK4(p1, 0, pa2); A128_PK4(p1, 8, pa3);
;     ...
; }
; __device__ __forceinline__ void qkt(f32x16& p0, f32x16& p1, const char* Ks, const bf16x8* qr, int r32, int hi) {
; #pragma unroll
;   for (int i = 0; i < 16; ++i) { p0[i] = 0.f; p1[i] = 0.f; }
; #pragma unroll
;   for (int d0 = 0; d0 < 4; ++d0) { const int cb = (d0 * 16 + hi * 8) * 2;
;     const bf16x8 b0 = *reinterpret_cast<const bf16x8*>(Ks + A128_KSWZ(r32, cb));
;     const bf16x8 b1 = *reinterpret_cast<const bf16x8*>(Ks + A128_KSWZ(32 + r32, cb));
;     p0 = __builtin_amdgcn_mfma_f32_32x32x16_bf16(b0, qr[d0], p0, 0, 0, 0);
;     p1 = __builtin_amdgcn_mfma_f32_32x32x16_bf16(b1, qr[d0], p1, 0, 0, 0); }
.LBB0_1119:
	v_exp_f32_e32 v178, v112
	v_exp_f32_e32 v179, v113
	v_exp_f32_e32 v194, v114
	v_exp_f32_e32 v195, v115
	v_exp_f32_e32 v196, v116
	v_exp_f32_e32 v197, v117
	v_exp_f32_e32 v198, v118
	v_exp_f32_e32 v199, v119
	v_exp_f32_e32 v210, v120
	v_exp_f32_e32 v211, v121
	v_exp_f32_e32 v212, v122
	v_exp_f32_e32 v213, v123
	v_exp_f32_e32 v214, v124
	v_exp_f32_e32 v215, v125
	v_exp_f32_e32 v216, v126
	v_exp_f32_e32 v217, v127
	s_waitcnt lgkmcnt(0)
	s_barrier
	ds_read_b128 v[80:83], v204 offset:32768
	ds_read_b128 v[84:87], v204 offset:36864
	ds_read_b128 v[170:173], v205 offset:32768
	ds_read_b128 v[174:177], v205 offset:36864
	ds_read_b128 v[232:235], v192 offset:32768
	ds_read_b128 v[236:239], v192 offset:36864
	v_exp_f32_e32 v104, v104
	v_exp_f32_e32 v105, v105
	s_waitcnt lgkmcnt(5)
	v_mfma_f32_32x32x16_bf16 v[112:127], v[80:83], v[140:143], 0
	v_exp_f32_e32 v106, v106
	v_exp_f32_e32 v107, v107
	v_exp_f32_e32 v226, v108
	v_exp_f32_e32 v227, v109
	v_exp_f32_e32 v228, v110
	v_exp_f32_e32 v229, v111
	v_pk_add_f32 v[108:109], v[104:105], v[210:211]
	s_waitcnt lgkmcnt(4)
	v_mfma_f32_32x32x16_bf16 v[80:95], v[84:87], v[140:143], 0
	v_add_f32_e64 v166, v226, v214
	v_add_f32_e64 v167, v227, v215
	s_waitcnt lgkmcnt(3)
	v_mfma_f32_32x32x16_bf16 v[112:127], v[170:173], v[136:139], v[112:127]
	s_waitcnt lgkmcnt(2)
	v_mfma_f32_32x32x16_bf16 v[80:95], v[174:177], v[136:139], v[80:95]
	ds_read_b128 v[170:173], v193 offset:32768
	ds_read_b128 v[174:177], v193 offset:36864
	s_waitcnt lgkmcnt(3)
	v_mfma_f32_32x32x16_bf16 v[112:127], v[232:235], v[132:135], v[112:127]
	s_waitcnt lgkmcnt(2)
	v_mfma_f32_32x32x16_bf16 v[80:95], v[236:239], v[132:135], v[80:95]
	s_waitcnt lgkmcnt(1)
	v_mfma_f32_32x32x16_bf16 v[112:127], v[170:173], v[128:131], v[112:127]
	v_exp_f32_e32 v170, v96
	v_exp_f32_e32 v171, v97
	v_exp_f32_e32 v172, v98
	v_exp_f32_e32 v173, v99
	v_pk_add_f32 v[96:97], v[106:107], v[212:213]
	v_pk_add_f32 v[110:111], v[170:171], v[178:179]
	v_pk_add_f32 v[98:99], v[172:173], v[194:195]
	s_waitcnt lgkmcnt(0)
	v_mfma_f32_32x32x16_bf16 v[80:95], v[174:177], v[128:131], v[80:95]
	v_exp_f32_e32 v174, v100
	v_exp_f32_e32 v175, v101
	v_exp_f32_e32 v176, v102
	v_exp_f32_e32 v177, v103
	v_pk_add_f32 v[100:101], v[228:229], v[216:217]
	v_pk_add_f32 v[208:209], v[174:175], v[196:197]
	v_pk_add_f32 v[108:109], v[110:111], v[108:109]
	v_pk_add_f32 v[102:103], v[176:177], v[198:199]
	v_pk_add_f32 v[166:167], v[208:209], v[166:167]
	v_pk_add_f32 v[100:101], v[102:103], v[100:101]
	v_pk_add_f32 v[96:97], v[98:99], v[96:97]
	v_pk_add_f32 v[98:99], v[108:109], v[166:167]
	v_pk_add_f32 v[96:97], v[96:97], v[100:101]
	s_nop 0
	v_pk_add_f32 v[96:97], v[98:99], v[96:97]
	s_nop 0
	v_pk_add_f32 v[166:167], v[96:97], v[96:97] op_sel:[0,1] op_sel_hi:[1,0]
	v_cvt_pk_bf16_f32 v96, v178, v179
	v_cvt_pk_bf16_f32 v97, v194, v195
	v_cvt_pk_bf16_f32 v98, v196, v197
	v_cvt_pk_bf16_f32 v99, v198, v199
	v_cvt_pk_bf16_f32 v100, v210, v211
	s_nop 0
	v_mov_b32_e32 v208, v166
	s_nop 1
	v_permlane32_swap_b32_e32 v166, v208
	v_cvt_pk_bf16_f32 v101, v212, v213
	v_cvt_pk_bf16_f32 v102, v214, v215
	v_cvt_pk_bf16_f32 v103, v216, v217
	v_cvt_pk_bf16_f32 v108, v170, v171
	v_cvt_pk_bf16_f32 v109, v172, v173
	v_cvt_pk_bf16_f32 v110, v174, v175
	v_cvt_pk_bf16_f32 v111, v176, v177
	v_cvt_pk_bf16_f32 v104, v104, v105
	v_cvt_pk_bf16_f32 v105, v106, v107
	v_cvt_pk_bf16_f32 v106, v226, v227
	v_cvt_pk_bf16_f32 v107, v228, v229
	s_cmp_ge_u32 s38, s27
	s_cselect_b64 s[2:3], -1, 0
	s_and_b64 vcc, exec, s[2:3]
	s_cbranch_vccnz .Latt_noload_a
	v_add_co_u32_e32 v144, vcc, 0xe481000, v162
	s_nop 1
	v_addc_co_u32_e32 v145, vcc, 0, v163, vcc
	v_add_co_u32_e32 v146, vcc, 0xe551000, v162
	s_nop 1
	v_addc_co_u32_e32 v147, vcc, 0, v163, vcc
	global_load_dwordx4 v[152:155], v[144:145], off
	global_load_dwordx4 v[148:151], v[146:147], off
	v_add_co_u32_e32 v144, vcc, 0xe480000, v164
	s_nop 1
	v_addc_co_u32_e32 v145, vcc, 0, v165, vcc
	global_load_dwordx4 v[144:147], v[144:145], off offset:2048
; template <bool FIRST = false>
; __device__ __forceinline__ void partialSM(f32x16& p0, f32x16& p1, float& m_reg, float& mn, float& alpha, const bool nomax) {
;   if (nomax) { mn = 0.f; alpha = 1.f;
; #pragma unroll
;     for (int r = 0; r < 16; ++r) p0[r] = __builtin_amdgcn_exp2f(p0[r]);
;     return; }
;   float pmax = p0[0];
; #pragma unroll
;   for (int r = 1; r < 16; ++r) pmax = fmaxf(pmax, p0[r]);
; #pragma unroll
;   for (int r = 0; r < 16; ++r) pmax = fmaxf(pmax, p1[r]);
;   { auto rr = __builtin_amdgcn_permlane32_swap(__float_as_uint(pmax), __float_as_uint(pmax), false, false); pmax = fmaxf(__uint_as_float(rr[0]), __uint_as_float(rr[1])); }
;   if (FIRST) { m_reg = (__builtin_fabsf(pmax) <= THRL) ? 0.f : pmax; mn = m_reg; alpha = 1.f; }
;   else if (__builtin_expect(__all(pmax - m_reg <= THRL), 1)) { mn = m_reg; alpha = 1.f; }
;   else { mn = fmaxf(m_reg, pmax); alpha = __builtin_amdgcn_exp2f(m_reg - mn); m_reg = mn; }
;   if (__builtin_expect(__any(mn != 0.f), 0)) {
; #pragma unroll
;     for (int r = 0; r < 16; ++r) { p0[r] = p0[r] - mn; p1[r] = p1[r] - mn; } }
; #pragma unroll
;   for (int r = 0; r < 16; ++r) p0[r] = __builtin_amdgcn_exp2f(p0[r]);
; }
; __device__ __forceinline__ void finishSM(f32x16& p0, f32x16& p1, float alpha, float& l_reg, bf16x8& pa0, bf16x8& pa1, bf16x8& pa2, bf16x8& pa3) {
; #pragma unroll
;   for (int r = 0; r < 16; ++r) p1[r] = __builtin_amdgcn_exp2f(p1[r]);
;   typedef float f32x8_ __attribute__((ext_vector_type(8))); typedef float f32x2_ __attribute__((ext_vector_type(2)));
;   const f32x16 s16_ = p0 + p1; const f32x8_ s8_ = s16_.lo + s16_.hi; const f32x4 s4_ = s8_.lo + s8_.hi; const f32x2_ s2_ = s4_.lo + s4_.hi;
;   float ps = s2_.x + s2_.y;
;   { auto rr = __builtin_amdgcn_permlane32_swap(__float_as_uint(ps), __float_as_uint(ps), false, false); ps = __uint_as_float(rr[0]) + __uint_as_float(rr[1]); }
;   l_reg = l_reg * alpha + ps;
;     ...
;   A128_PK4(p0, 0, pa0); A128_PK4(p0, 8, pa1); A128_PK4(p1, 0, pa2); A128_PK4(p1, 8, pa3);
;     ...
; }
; __device__ __forceinline__ void qkt(f32x16& p0, f32x16& p1, const char* Ks, const bf16x8* qr, int r32, int hi) {
; #pragma unroll
;   for (int i = 0; i < 16; ++i) { p0[i] = 0.f; p1[i] = 0.f; }
; #pragma unroll
;   for (int d0 = 0; d0 < 4; ++d0) { const int cb = (d0 * 16 + hi * 8) * 2;
;     const bf16x8 b0 = *reinterpret_cast<const bf16x8*>(Ks + A128_KSWZ(r32, cb));
.LBB0_1121:
	ds_read_b64_tr_b16 v[162:163], v189 offset:0
	ds_read_b64_tr_b16 v[164:165], v189 offset:0x800
	ds_read_b64_tr_b16 v[170:171], v189 offset:0x1000
	ds_read_b64_tr_b16 v[172:173], v189 offset:0x1800
	ds_read_b64_tr_b16 v[174:175], v189 offset:0x2000
	ds_read_b64_tr_b16 v[176:177], v189 offset:0x2800
	ds_read_b64_tr_b16 v[194:195], v189 offset:0x3000
	ds_read_b64_tr_b16 v[196:197], v189 offset:0x3800
	ds_read_b64_tr_b16 v[232:233], v189 offset:0x200
	ds_read_b64_tr_b16 v[234:235], v189 offset:0xa00
	ds_read_b64_tr_b16 v[236:237], v189 offset:0x1200
	ds_read_b64_tr_b16 v[238:239], v189 offset:0x1a00
	ds_read_b64_tr_b16 v[240:241], v189 offset:0x2200
	ds_read_b64_tr_b16 v[242:243], v189 offset:0x2a00
	ds_read_b64_tr_b16 v[244:245], v189 offset:0x3200
	ds_read_b64_tr_b16 v[246:247], v189 offset:0x3a00
	s_waitcnt lgkmcnt(8)
	s_nop 0
	v_mfma_f32_32x32x16_bf16 v[16:31], v[96:99], v[162:165], v[16:31]
	ds_read_b64_tr_b16 v[162:163], v189 offset:0x400
	ds_read_b64_tr_b16 v[164:165], v189 offset:0xc00
	v_mfma_f32_32x32x16_bf16 v[16:31], v[100:103], v[170:173], v[16:31]
	ds_read_b64_tr_b16 v[170:171], v189 offset:0x1400
	ds_read_b64_tr_b16 v[172:173], v189 offset:0x1c00
	v_mfma_f32_32x32x16_bf16 v[16:31], v[108:111], v[174:177], v[16:31]
	ds_read_b64_tr_b16 v[174:175], v189 offset:0x2400
	ds_read_b64_tr_b16 v[176:177], v189 offset:0x2c00
	v_mfma_f32_32x32x16_bf16 v[16:31], v[104:107], v[194:197], v[16:31]
	ds_read_b64_tr_b16 v[194:195], v189 offset:0x3400
	ds_read_b64_tr_b16 v[196:197], v189 offset:0x3c00
	s_waitcnt lgkmcnt(8)
	v_mfma_f32_32x32x16_bf16 v[32:47], v[96:99], v[232:235], v[32:47]
	ds_read_b64_tr_b16 v[232:233], v189 offset:0x600
	ds_read_b64_tr_b16 v[234:235], v189 offset:0xe00
	v_mfma_f32_32x32x16_bf16 v[32:47], v[100:103], v[236:239], v[32:47]
	ds_read_b64_tr_b16 v[236:237], v189 offset:0x1600
	ds_read_b64_tr_b16 v[238:239], v189 offset:0x1e00
	v_mfma_f32_32x32x16_bf16 v[32:47], v[108:111], v[240:243], v[32:47]
	ds_read_b64_tr_b16 v[240:241], v189 offset:0x2600
	ds_read_b64_tr_b16 v[242:243], v189 offset:0x2e00
	v_mfma_f32_32x32x16_bf16 v[32:47], v[104:107], v[244:247], v[32:47]
	ds_read_b64_tr_b16 v[244:245], v189 offset:0x3600
	ds_read_b64_tr_b16 v[246:247], v189 offset:0x3e00
	s_waitcnt lgkmcnt(8)
	v_mfma_f32_32x32x16_bf16 v[48:63], v[96:99], v[162:165], v[48:63]
	v_mfma_f32_32x32x16_bf16 v[48:63], v[100:103], v[170:173], v[48:63]
	v_mfma_f32_32x32x16_bf16 v[48:63], v[108:111], v[174:177], v[48:63]
	v_mfma_f32_32x32x16_bf16 v[48:63], v[104:107], v[194:197], v[48:63]
	s_waitcnt lgkmcnt(0)
	v_mfma_f32_32x32x16_bf16 v[64:79], v[96:99], v[232:235], v[64:79]
	v_mov_b32_e32 v15, 1.0
	s_and_b64 vcc, exec, s[4:5]
	v_mfma_f32_32x32x16_bf16 v[64:79], v[100:103], v[236:239], v[64:79]
	v_mfma_f32_32x32x16_bf16 v[64:79], v[108:111], v[240:243], v[64:79]
	v_mfma_f32_32x32x16_bf16 v[64:79], v[104:107], v[244:247], v[64:79]
	s_cbranch_vccnz .LBB0_1124
	v_max_f32_e32 v15, v113, v113
	v_max_f32_e32 v96, v112, v112
	v_max_f32_e32 v15, v96, v15
	v_max3_f32 v15, v15, v114, v115
	v_max3_f32 v15, v15, v116, v117
	v_max3_f32 v15, v15, v118, v119
	v_max3_f32 v15, v15, v120, v121
	v_max3_f32 v15, v15, v122, v123
	v_max3_f32 v15, v15, v124, v125
	v_max3_f32 v15, v15, v126, v127
	v_max3_f32 v15, v15, v80, v81
	v_max3_f32 v15, v15, v82, v83
	v_max3_f32 v15, v15, v84, v85
	v_max3_f32 v15, v15, v86, v87
	v_max3_f32 v15, v15, v88, v89
	v_max3_f32 v15, v15, v90, v91
	v_max3_f32 v15, v15, v92, v93
	v_max3_f32 v15, v15, v94, v95
	v_mov_b32_e32 v96, v15
	s_nop 1
	v_permlane32_swap_b32_e32 v15, v96
	v_max_f32_e32 v96, v96, v96
	v_max_f32_e32 v15, v15, v15
	v_max_f32_e32 v15, v15, v96
	v_sub_f32_e32 v96, v15, v168
	v_cmp_ge_f32_e32 vcc, s74, v96
	s_cmp_eq_u64 vcc, exec
	v_max_f32_e32 v96, v168, v168
	v_max_f32_e32 v15, v96, v15
	s_cselect_b64 s[6:7], -1, 0
	v_cndmask_b32_e64 v167, v15, v168, s[6:7]
	v_cmp_neq_f32_e32 vcc, 0, v167
	s_cbranch_vccnz .LBB0_1133

; #define A128_SWRITE(b, i) do { *(bf16x8*)(V_lds + (b) * SHM_V + vst0) = sr_[i].vs0; *(bf16x8*)(V_lds + (b) * SHM_V + vst1) = sr_[i].vs1; *(bf16x8*)(K_lds + (b) * SHM_K + kst) = sr_[i].ks0; } while (0)
; #define A128_SWAIT() asm volatile("s_waitcnt vmcnt(3)" ::: "memory")
; #define A128_RESC(a) do { if (__any((a) < 1.f)) { if (hi == 0) al_l[r32] = (a); asm volatile("s_waitcnt lgkmcnt(0)" ::: "memory"); \
;     _Pragma("unroll") for (int d = 0; d < 4; ++d) _Pragma("unroll") for (int r = 0; r < 16; ++r) o[d][r] *= al_l[crow(r, hi)]; } } while (0)
; __device__ __forceinline__ void unit(const bf16* __restrict__ Qb0, const bf16* __restrict__ Kh0, const bf16* __restrict__ Vh, bf16_t* Ob, int seq, char* lds, const int tid_in, const float lam, const float onem, const float* __restrict__ subw, const float* __restrict__ kmb  ) {
;     ...
;     __syncthreads(); A128_SWAIT(); A128_SWRITE(1, 1);
;     if (!nomax) A128_RESC(alA); __syncthreads();
.LBB0_1125:
	s_barrier
	s_waitcnt vmcnt(3)
	s_and_b64 vcc, exec, s[4:5]
	ds_write_b128 v191, v[2:5] offset:16384
	ds_write_b128 v202, v[6:9] offset:16384
	ds_write_b128 v203, v[10:13] offset:40960
	s_cbranch_vccnz .LBB0_1130
	v_cmp_gt_f32_e32 vcc, 1.0, v15
	s_cbranch_vccz .LBB0_1130
	s_and_saveexec_b64 s[6:7], s[0:1]
	ds_write_b32 v188, v15 offset:49280
	s_or_b64 exec, exec, s[6:7]
	s_waitcnt lgkmcnt(0)
	v_add_u32_e32 v96, s37, v156
	ds_read_b128 v[2:5], v96 offset:49376
	ds_read_b128 v[6:9], v96 offset:49344
	ds_read_b128 v[10:13], v96 offset:49312
	ds_read_b128 v[96:99], v96 offset:49280
	s_waitcnt lgkmcnt(3)
	v_pk_mul_f32 v[28:29], v[28:29], v[2:3]
	s_waitcnt lgkmcnt(2)
	v_pk_mul_f32 v[24:25], v[24:25], v[6:7]
	s_waitcnt lgkmcnt(1)
	v_pk_mul_f32 v[20:21], v[20:21], v[10:11]
	v_pk_mul_f32 v[30:31], v[30:31], v[4:5]
	v_pk_mul_f32 v[26:27], v[26:27], v[8:9]
	v_pk_mul_f32 v[22:23], v[22:23], v[12:13]
	s_waitcnt lgkmcnt(0)
	v_pk_mul_f32 v[18:19], v[18:19], v[98:99]
	v_pk_mul_f32 v[16:17], v[16:17], v[96:97]
	v_pk_mul_f32 v[44:45], v[44:45], v[2:3]
	v_pk_mul_f32 v[40:41], v[40:41], v[6:7]
	v_pk_mul_f32 v[36:37], v[36:37], v[10:11]
	v_pk_mul_f32 v[46:47], v[46:47], v[4:5]
	v_pk_mul_f32 v[42:43], v[42:43], v[8:9]
	v_pk_mul_f32 v[38:39], v[38:39], v[12:13]
	v_pk_mul_f32 v[34:35], v[34:35], v[98:99]
	v_pk_mul_f32 v[32:33], v[32:33], v[96:97]
	v_pk_mul_f32 v[60:61], v[60:61], v[2:3]
	v_pk_mul_f32 v[56:57], v[56:57], v[6:7]
	v_pk_mul_f32 v[52:53], v[52:53], v[10:11]
	v_pk_mul_f32 v[62:63], v[62:63], v[4:5]
	v_pk_mul_f32 v[58:59], v[58:59], v[8:9]
	v_pk_mul_f32 v[54:55], v[54:55], v[12:13]
	v_pk_mul_f32 v[50:51], v[50:51], v[98:99]
	v_pk_mul_f32 v[48:49], v[48:49], v[96:97]
	v_pk_mul_f32 v[76:77], v[76:77], v[2:3]
	v_pk_mul_f32 v[72:73], v[72:73], v[6:7]
	v_pk_mul_f32 v[68:69], v[68:69], v[10:11]
	v_pk_mul_f32 v[78:79], v[78:79], v[4:5]
	v_pk_mul_f32 v[74:75], v[74:75], v[8:9]
	v_pk_mul_f32 v[70:71], v[70:71], v[12:13]
	v_pk_mul_f32 v[66:67], v[66:67], v[98:99]
	v_pk_mul_f32 v[64:65], v[64:65], v[96:97]

; #define A128_SBAR() __builtin_amdgcn_sched_barrier(0)
; #define A128_SLOAD(i, k0) do { sr_[i].vs0 = *reinterpret_cast<const bf16x8*>(&Vh[(long)((k0) + sr) * LDK + sc]); sr_[i].vs1 = *reinterpret_cast<const bf16x8*>(&Vh[(long)((k0) + 32 + sr) * LDK + sc]); \
;     sr_[i].ks0 = *reinterpret_cast<const bf16x8*>(&Kh[(long)((k0) + kr) * LDK + kc]); } while (0)
; __device__ __forceinline__ void unit(const bf16* __restrict__ Qb0, const bf16* __restrict__ Kh0, const bf16* __restrict__ Vh, bf16_t* Ob, int seq, char* lds, const int tid_in, const float lam, const float onem, const float* __restrict__ subw, const float* __restrict__ kmb  ) {
;     ...
;     if (j + 3 < NT) A128_SLOAD(0, (j + 3) * KVBLK); A128_SBAR();
;     pv_d0(o, vb0 + (int)SHM_V, pa0, pa1, pa2, pa3); partialSM(pA0, pA1, m_reg, mnA, alA, nomax);
.Latt_noload_a:
	s_waitcnt vmcnt(0)
	s_branch .LBB0_1121

; #define PG8_LDA(dst, b, h) do { _Pragma("unroll") for (int m = 0; m < 4; ++m) _Pragma("unroll") for (int k = 0; k < 2; ++k) dst[m][k] = *(const LAS bf16x8*)(lds + PG8_SA(b, h) + aoff + m * 2048 + k * 1024); } while (0)
; #define PG8_BAR __builtin_amdgcn_s_barrier()
;     ...
;         const bool has_next = S.next(ui + 1, nxt);
;         const char* nA = PG8_UNI(has_next ? nxt.a : cA); const char* nB = PG8_UNI(has_next ? nxt.b : cB);
;         const int nt = cur.kt;
;         for (int t = 0; t < nt; t += 2) {
;             const bool last = (t == nt - 2);
;             if constexpr (HOOK) { if (t == 16 || t == 32) E.mid(acc, cur, t >> 4, wr, wc); }
;             const char* a1 = cA + (size_t)(t + 1) * kstepA;
;             const char* a2 = last ? nA : cA + (size_t)(t + 2) * kstepA; const char* b2 = last ? nB : cB + (size_t)(t + 2) * kstep;
;             const char* a3 = a2 + kstepA; const char* b3 = b2 + kstep;
;             PG8_LDB(B0, 0, 0); PG8_LDB(B1, 0, 1); PG8_SCHED; PG8_LDA(At, 0, 0); PG8_STAGE(PG8_SA(1, 1), a1 + hstepA, voffA);
;             PG8_WAIT_V(8); PG8_WAIT_L(0); PG8_BAR; PG8_MMA(0, 0, At, B0); PG8_MMA(0, 1, At, B1); PG8_BAR; PG8_SCHED;
;             PG8_LDA(At, 0, 1); PG8_STAGE(PG8_SB(0, 0), b2, voffB); PG8_STAGE(PG8_SB(0, 1), b2 + hstepB, voffB); PG8_STAGE(PG8_SA(0, 0), a2, voffA);
;             PG8_WAIT_V(8); PG8_WAIT_L(0); PG8_BAR; PG8_MMA(1, 0, At, B0); PG8_MMA(1, 1, At, B1); PG8_BAR; PG8_SCHED;
;             PG8_LDB(B0, 1, 0); PG8_LDB(B1, 1, 1); PG8_SCHED; PG8_LDA(At, 1, 0); PG8_STAGE(PG8_SA(0, 1), a2 + hstepA, voffA);
;             PG8_WAIT_V(8); PG8_WAIT_L(0); PG8_BAR; PG8_MMA(0, 0, At, B0); PG8_MMA(0, 1, At, B1); PG8_BAR; PG8_SCHED;
;             PG8_LDA(At, 1, 1); PG8_STAGE(PG8_SB(1, 0), b3, voffB); PG8_STAGE(PG8_SB(1, 1), b3 + hstepB, voffB); PG8_STAGE(PG8_SA(1, 0), a3, voffA);
;             PG8_WAIT_V(8); PG8_WAIT_L(0); PG8_BAR; PG8_MMA(1, 0, At, B0); PG8_MMA(1, 1, At, B1); PG8_BAR; PG8_SCHED;
;         }
;         if (wr == 0) PG8_BAR;
;         E(acc, cur, wr, wc, fr, fq);
;         if (!has_next) break;
; #pragma unroll
;         for (int a = 0; a < 2; ++a)
; #pragma unroll
;             for (int b = 0; b < 2; ++b)
; #pragma unroll
;                 for (int m = 0; m < 4; ++m)
; #pragma unroll
;                     for (int n = 0; n < 2; ++n) acc[a][b][m][n] = (f32x4){0.f, 0.f, 0.f, 0.f};
;         cur = nxt; cA = nA; cB = nB; ++ui;
.LBB0_1309:
	v_mov_b32_e32 v2, s2
	v_cndmask_b32_e64 v2, v2, v150, s[16:17]
	v_mov_b32_e32 v3, s3
	s_add_i32 s55, s54, -2
	v_cndmask_b32_e64 v3, v3, v151, s[16:17]
	v_readfirstlane_b32 s18, v2
	v_mov_b32_e32 v2, s22
	s_add_u32 s56, s22, 0x100
	v_readfirstlane_b32 s19, v3
	v_cndmask_b32_e64 v2, v2, v152, s[16:17]
	v_mov_b32_e32 v3, s23
	s_addc_u32 s57, s23, 0
	v_cndmask_b32_e64 v3, v3, v153, s[16:17]
	v_readfirstlane_b32 s20, v2
	s_add_u32 s2, s2, 0x340080
	v_mov_b32_e32 v2, 0
	v_readfirstlane_b32 s21, v3
	s_addc_u32 s3, s3, 0
	s_mov_b32 s22, 0
	v_mov_b32_e32 v3, v2
	v_mov_b32_e32 v4, v2
	v_mov_b32_e32 v5, v2
	v_mov_b32_e32 v6, v2
	v_mov_b32_e32 v7, v2
	v_mov_b32_e32 v8, v2
	v_mov_b32_e32 v9, v2
	v_mov_b32_e32 v18, v2
	v_mov_b32_e32 v19, v2
	v_mov_b32_e32 v20, v2
	v_mov_b32_e32 v21, v2
	v_mov_b32_e32 v22, v2
	v_mov_b32_e32 v23, v2
	v_mov_b32_e32 v24, v2
	v_mov_b32_e32 v25, v2
	v_mov_b32_e32 v42, v2
	v_mov_b32_e32 v43, v2
	v_mov_b32_e32 v44, v2
	v_mov_b32_e32 v45, v2
	v_mov_b32_e32 v50, v2
	v_mov_b32_e32 v51, v2
	v_mov_b32_e32 v52, v2
	v_mov_b32_e32 v53, v2
	v_mov_b32_e32 v66, v2
	v_mov_b32_e32 v67, v2
	v_mov_b32_e32 v68, v2
	v_mov_b32_e32 v69, v2
	v_mov_b32_e32 v70, v2
	v_mov_b32_e32 v71, v2
	v_mov_b32_e32 v72, v2
	v_mov_b32_e32 v73, v2
	v_mov_b32_e32 v10, v2
	v_mov_b32_e32 v11, v2
	v_mov_b32_e32 v12, v2
	v_mov_b32_e32 v13, v2
	v_mov_b32_e32 v14, v2
	v_mov_b32_e32 v15, v2
	v_mov_b32_e32 v16, v2
	v_mov_b32_e32 v17, v2
	v_mov_b32_e32 v26, v2
	v_mov_b32_e32 v27, v2
	v_mov_b32_e32 v28, v2
	v_mov_b32_e32 v29, v2
	v_mov_b32_e32 v34, v2
	v_mov_b32_e32 v35, v2
	v_mov_b32_e32 v36, v2
	v_mov_b32_e32 v37, v2
	v_mov_b32_e32 v58, v2
	v_mov_b32_e32 v59, v2
	v_mov_b32_e32 v60, v2
	v_mov_b32_e32 v61, v2
	v_mov_b32_e32 v62, v2
	v_mov_b32_e32 v63, v2
	v_mov_b32_e32 v64, v2
	v_mov_b32_e32 v65, v2
	v_mov_b32_e32 v74, v2
	v_mov_b32_e32 v75, v2
	v_mov_b32_e32 v76, v2
	v_mov_b32_e32 v77, v2
	v_mov_b32_e32 v78, v2
	v_mov_b32_e32 v79, v2
	v_mov_b32_e32 v80, v2
	v_mov_b32_e32 v81, v2
	v_mov_b32_e32 v82, v2
	v_mov_b32_e32 v83, v2
	v_mov_b32_e32 v84, v2
	v_mov_b32_e32 v85, v2
	v_mov_b32_e32 v86, v2
	v_mov_b32_e32 v87, v2
	v_mov_b32_e32 v88, v2
	v_mov_b32_e32 v89, v2
	v_mov_b32_e32 v98, v2
	v_mov_b32_e32 v99, v2
	v_mov_b32_e32 v100, v2
	v_mov_b32_e32 v101, v2
	v_mov_b32_e32 v102, v2
	v_mov_b32_e32 v103, v2
	v_mov_b32_e32 v104, v2
	v_mov_b32_e32 v105, v2
	v_mov_b32_e32 v114, v2
	v_mov_b32_e32 v115, v2
	v_mov_b32_e32 v116, v2
	v_mov_b32_e32 v117, v2
	v_mov_b32_e32 v118, v2
	v_mov_b32_e32 v119, v2
	v_mov_b32_e32 v120, v2
	v_mov_b32_e32 v121, v2
	v_mov_b32_e32 v130, v2
	v_mov_b32_e32 v131, v2
	v_mov_b32_e32 v132, v2
	v_mov_b32_e32 v133, v2
	v_mov_b32_e32 v134, v2
	v_mov_b32_e32 v135, v2
	v_mov_b32_e32 v136, v2
	v_mov_b32_e32 v137, v2
	v_mov_b32_e32 v90, v2
	v_mov_b32_e32 v91, v2
	v_mov_b32_e32 v92, v2
	v_mov_b32_e32 v93, v2
	v_mov_b32_e32 v94, v2
	v_mov_b32_e32 v95, v2
	v_mov_b32_e32 v96, v2
	v_mov_b32_e32 v97, v2
	v_mov_b32_e32 v106, v2
	v_mov_b32_e32 v107, v2
	v_mov_b32_e32 v108, v2
	v_mov_b32_e32 v109, v2
	v_mov_b32_e32 v110, v2
	v_mov_b32_e32 v111, v2
	v_mov_b32_e32 v112, v2
	v_mov_b32_e32 v113, v2
	v_mov_b32_e32 v122, v2
	v_mov_b32_e32 v123, v2
	v_mov_b32_e32 v124, v2
	v_mov_b32_e32 v125, v2
	v_mov_b32_e32 v126, v2
	v_mov_b32_e32 v127, v2
	v_mov_b32_e32 v128, v2
	v_mov_b32_e32 v129, v2
	v_mov_b32_e32 v138, v2
	v_mov_b32_e32 v139, v2
	v_mov_b32_e32 v140, v2
	v_mov_b32_e32 v141, v2
	v_mov_b32_e32 v142, v2
	v_mov_b32_e32 v143, v2
	v_mov_b32_e32 v144, v2
	v_mov_b32_e32 v145, v2

; #define PG8_LDA(dst, b, h) do { _Pragma("unroll") for (int m = 0; m < 4; ++m) _Pragma("unroll") for (int k = 0; k < 2; ++k) dst[m][k] = *(const LAS bf16x8*)(lds + PG8_SA(b, h) + aoff + m * 2048 + k * 1024); } while (0)
; #define PG8_BAR __builtin_amdgcn_s_barrier()
;     ...
;         const bool has_next = S.next(ui + 1, nxt);
;         const char* nA = PG8_UNI(has_next ? nxt.a : cA); const char* nB = PG8_UNI(has_next ? nxt.b : cB);
;         const int nt = cur.kt;
;         for (int t = 0; t < nt; t += 2) {
;             const bool last = (t == nt - 2);
;             if constexpr (HOOK) { if (t == 16 || t == 32) E.mid(acc, cur, t >> 4, wr, wc); }
;             const char* a1 = cA + (size_t)(t + 1) * kstepA;
;             const char* a2 = last ? nA : cA + (size_t)(t + 2) * kstepA; const char* b2 = last ? nB : cB + (size_t)(t + 2) * kstep;
;             const char* a3 = a2 + kstepA; const char* b3 = b2 + kstep;
;             PG8_LDB(B0, 0, 0); PG8_LDB(B1, 0, 1); PG8_SCHED; PG8_LDA(At, 0, 0); PG8_STAGE(PG8_SA(1, 1), a1 + hstepA, voffA);
;             PG8_WAIT_V(8); PG8_WAIT_L(0); PG8_BAR; PG8_MMA(0, 0, At, B0); PG8_MMA(0, 1, At, B1); PG8_BAR; PG8_SCHED;
;             PG8_LDA(At, 0, 1); PG8_STAGE(PG8_SB(0, 0), b2, voffB); PG8_STAGE(PG8_SB(0, 1), b2 + hstepB, voffB); PG8_STAGE(PG8_SA(0, 0), a2, voffA);
;             PG8_WAIT_V(8); PG8_WAIT_L(0); PG8_BAR; PG8_MMA(1, 0, At, B0); PG8_MMA(1, 1, At, B1); PG8_BAR; PG8_SCHED;
;             PG8_LDB(B0, 1, 0); PG8_LDB(B1, 1, 1); PG8_SCHED; PG8_LDA(At, 1, 0); PG8_STAGE(PG8_SA(0, 1), a2 + hstepA, voffA);
;             PG8_WAIT_V(8); PG8_WAIT_L(0); PG8_BAR; PG8_MMA(0, 0, At, B0); PG8_MMA(0, 1, At, B1); PG8_BAR; PG8_SCHED;
;             PG8_LDA(At, 1, 1); PG8_STAGE(PG8_SB(1, 0), b3, voffB); PG8_STAGE(PG8_SB(1, 1), b3 + hstepB, voffB); PG8_STAGE(PG8_SA(1, 0), a3, voffA);
;             PG8_WAIT_V(8); PG8_WAIT_L(0); PG8_BAR; PG8_MMA(1, 0, At, B0); PG8_MMA(1, 1, At, B1); PG8_BAR; PG8_SCHED;
;         }
;         if (wr == 0) PG8_BAR;
;         E(acc, cur, wr, wc, fr, fq);
;         if (!has_next) break;
; #pragma unroll
;         for (int a = 0; a < 2; ++a)
; #pragma unroll
;             for (int b = 0; b < 2; ++b)
; #pragma unroll
;                 for (int m = 0; m < 4; ++m)
; #pragma unroll
;                     for (int n = 0; n < 2; ++n) acc[a][b][m][n] = (f32x4){0.f, 0.f, 0.f, 0.f};
;         cur = nxt; cA = nA; cB = nB; ++ui;
.LBB0_1386:
	v_mov_b32_e32 v2, s3
	s_lshl_b32 s25, s54, 9
	v_mov_b32_e32 v0, s2
	v_cndmask_b32_e64 v2, v2, v207, s[16:17]
	s_lshl_b32 s24, s55, 12
	s_add_i32 s57, s25, s47
	v_cndmask_b32_e64 v0, v0, v206, s[16:17]
	v_readfirstlane_b32 s19, v2
	v_mov_b32_e32 v2, s23
	s_add_i32 s58, s56, -2
	s_add_i32 s57, s57, s24
	v_readfirstlane_b32 s18, v0
	v_mov_b32_e32 v0, s22
	v_cndmask_b32_e64 v2, v2, v209, s[16:17]
	s_add_u32 s59, s22, 0x100
	v_cndmask_b32_e64 v0, v0, v208, s[16:17]
	v_readfirstlane_b32 s21, v2
	s_addc_u32 s60, s23, 0
	v_mov_b32_e32 v2, v1
	v_mov_b32_e32 v3, v1
	v_readfirstlane_b32 s20, v0
	s_add_u32 s2, s2, 0x340080
	v_mov_b32_e32 v0, v1
	v_mov_b64_e32 v[6:7], v[2:3]
	v_mov_b64_e32 v[10:11], v[2:3]
	v_mov_b64_e32 v[22:23], v[2:3]
	v_mov_b64_e32 v[26:27], v[2:3]
	v_mov_b64_e32 v[38:39], v[2:3]
	v_mov_b64_e32 v[42:43], v[2:3]
	v_mov_b64_e32 v[54:55], v[2:3]
	v_mov_b64_e32 v[58:59], v[2:3]
	v_mov_b64_e32 v[14:15], v[2:3]
	v_mov_b64_e32 v[18:19], v[2:3]
	v_mov_b64_e32 v[30:31], v[2:3]
	v_mov_b64_e32 v[34:35], v[2:3]
	v_mov_b64_e32 v[46:47], v[2:3]
	v_mov_b64_e32 v[50:51], v[2:3]
	v_mov_b64_e32 v[62:63], v[2:3]
	v_mov_b64_e32 v[66:67], v[2:3]
	v_mov_b64_e32 v[70:71], v[2:3]
	v_mov_b64_e32 v[74:75], v[2:3]
	v_mov_b64_e32 v[86:87], v[2:3]
	v_mov_b64_e32 v[90:91], v[2:3]
	v_mov_b64_e32 v[102:103], v[2:3]
	v_mov_b64_e32 v[106:107], v[2:3]
	v_mov_b64_e32 v[118:119], v[2:3]
	v_mov_b64_e32 v[122:123], v[2:3]
	v_mov_b64_e32 v[78:79], v[2:3]
	v_mov_b64_e32 v[82:83], v[2:3]
	v_mov_b64_e32 v[94:95], v[2:3]
	v_mov_b64_e32 v[98:99], v[2:3]
	v_mov_b64_e32 v[110:111], v[2:3]
	v_mov_b64_e32 v[114:115], v[2:3]
	v_mov_b64_e32 v[126:127], v[2:3]
	v_mov_b64_e32 v[130:131], v[2:3]
	s_addc_u32 s3, s3, 0
	s_mov_b32 s26, 0
	v_mov_b64_e32 v[4:5], v[0:1]
	v_mov_b64_e32 v[8:9], v[0:1]
	v_mov_b64_e32 v[20:21], v[0:1]
	v_mov_b64_e32 v[24:25], v[0:1]
	v_mov_b64_e32 v[36:37], v[0:1]
	v_mov_b64_e32 v[40:41], v[0:1]
	v_mov_b64_e32 v[52:53], v[0:1]
	v_mov_b64_e32 v[56:57], v[0:1]
	v_mov_b64_e32 v[12:13], v[0:1]
	v_mov_b64_e32 v[16:17], v[0:1]
	v_mov_b64_e32 v[28:29], v[0:1]
	v_mov_b64_e32 v[32:33], v[0:1]
	v_mov_b64_e32 v[44:45], v[0:1]
	v_mov_b64_e32 v[48:49], v[0:1]
	v_mov_b64_e32 v[60:61], v[0:1]
	v_mov_b64_e32 v[64:65], v[0:1]
	v_mov_b64_e32 v[68:69], v[0:1]
	v_mov_b64_e32 v[72:73], v[0:1]
	v_mov_b64_e32 v[84:85], v[0:1]
	v_mov_b64_e32 v[88:89], v[0:1]
	v_mov_b64_e32 v[100:101], v[0:1]
	v_mov_b64_e32 v[104:105], v[0:1]
	v_mov_b64_e32 v[116:117], v[0:1]
	v_mov_b64_e32 v[120:121], v[0:1]
	v_mov_b64_e32 v[76:77], v[0:1]
	v_mov_b64_e32 v[80:81], v[0:1]
	v_mov_b64_e32 v[92:93], v[0:1]
	v_mov_b64_e32 v[96:97], v[0:1]
	v_mov_b64_e32 v[108:109], v[0:1]
	v_mov_b64_e32 v[112:113], v[0:1]
	v_mov_b64_e32 v[124:125], v[0:1]
	v_mov_b64_e32 v[128:129], v[0:1]
	s_cmp_lt_i32 s26, 32
	s_cbranch_scc0 .LBB0_1393

; #define PG8_LDA(dst, b, h) do { _Pragma("unroll") for (int m = 0; m < 4; ++m) _Pragma("unroll") for (int k = 0; k < 2; ++k) dst[m][k] = *(const LAS bf16x8*)(lds + PG8_SA(b, h) + aoff + m * 2048 + k * 1024); } while (0)
; #define PG8_BAR __builtin_amdgcn_s_barrier()
;     ...
;         const bool has_next = S.next(ui + 1, nxt);
;         const char* nA = PG8_UNI(has_next ? nxt.a : cA); const char* nB = PG8_UNI(has_next ? nxt.b : cB);
;         const int nt = cur.kt;
;         for (int t = 0; t < nt; t += 2) {
;             const bool last = (t == nt - 2);
;             if constexpr (HOOK) { if (t == 16 || t == 32) E.mid(acc, cur, t >> 4, wr, wc); }
;             const char* a1 = cA + (size_t)(t + 1) * kstepA;
;             const char* a2 = last ? nA : cA + (size_t)(t + 2) * kstepA; const char* b2 = last ? nB : cB + (size_t)(t + 2) * kstep;
;             const char* a3 = a2 + kstepA; const char* b3 = b2 + kstep;
;             PG8_LDB(B0, 0, 0); PG8_LDB(B1, 0, 1); PG8_SCHED; PG8_LDA(At, 0, 0); PG8_STAGE(PG8_SA(1, 1), a1 + hstepA, voffA);
;             PG8_WAIT_V(8); PG8_WAIT_L(0); PG8_BAR; PG8_MMA(0, 0, At, B0); PG8_MMA(0, 1, At, B1); PG8_BAR; PG8_SCHED;
;             PG8_LDA(At, 0, 1); PG8_STAGE(PG8_SB(0, 0), b2, voffB); PG8_STAGE(PG8_SB(0, 1), b2 + hstepB, voffB); PG8_STAGE(PG8_SA(0, 0), a2, voffA);
;             PG8_WAIT_V(8); PG8_WAIT_L(0); PG8_BAR; PG8_MMA(1, 0, At, B0); PG8_MMA(1, 1, At, B1); PG8_BAR; PG8_SCHED;
;             PG8_LDB(B0, 1, 0); PG8_LDB(B1, 1, 1); PG8_SCHED; PG8_LDA(At, 1, 0); PG8_STAGE(PG8_SA(0, 1), a2 + hstepA, voffA);
;             PG8_WAIT_V(8); PG8_WAIT_L(0); PG8_BAR; PG8_MMA(0, 0, At, B0); PG8_MMA(0, 1, At, B1); PG8_BAR; PG8_SCHED;
;             PG8_LDA(At, 1, 1); PG8_STAGE(PG8_SB(1, 0), b3, voffB); PG8_STAGE(PG8_SB(1, 1), b3 + hstepB, voffB); PG8_STAGE(PG8_SA(1, 0), a3, voffA);
;             PG8_WAIT_V(8); PG8_WAIT_L(0); PG8_BAR; PG8_MMA(1, 0, At, B0); PG8_MMA(1, 1, At, B1); PG8_BAR; PG8_SCHED;
;         }
;         if (wr == 0) PG8_BAR;
;         E(acc, cur, wr, wc, fr, fq);
;         if (!has_next) break;
; #pragma unroll
;         for (int a = 0; a < 2; ++a)
; #pragma unroll
;             for (int b = 0; b < 2; ++b)
; #pragma unroll
;                 for (int m = 0; m < 4; ++m)
; #pragma unroll
;                     for (int n = 0; n < 2; ++n) acc[a][b][m][n] = (f32x4){0.f, 0.f, 0.f, 0.f};
;         cur = nxt; cA = nA; cB = nB; ++ui;
.LBB0_1488:
	s_and_b64 s[22:23], s[20:21], exec
	s_cselect_b32 s22, s16, s2
	s_cselect_b32 s23, s17, s3
	s_cselect_b32 s24, s18, s26
	s_cselect_b32 s25, s19, s27
	s_cmp_lt_i32 s73, 1
	s_cbranch_scc1 .LBB0_1495
	s_add_i32 s76, s73, -2
	s_add_u32 s77, s26, 0x100
	s_addc_u32 s78, s27, 0
	s_add_u32 s79, s2, 0x100
	v_mov_b32_e32 v2, 0
	s_addc_u32 s80, s3, 0
	s_mov_b32 s2, 0
	v_mov_b32_e32 v3, v2
	v_mov_b32_e32 v4, v2
	v_mov_b32_e32 v5, v2
	v_mov_b32_e32 v6, v2
	v_mov_b32_e32 v7, v2
	v_mov_b32_e32 v8, v2
	v_mov_b32_e32 v9, v2
	v_mov_b32_e32 v10, v2
	v_mov_b32_e32 v11, v2
	v_mov_b32_e32 v12, v2
	v_mov_b32_e32 v13, v2
	v_mov_b32_e32 v14, v2
	v_mov_b32_e32 v15, v2
	v_mov_b32_e32 v16, v2
	v_mov_b32_e32 v17, v2
	v_mov_b32_e32 v18, v2
	v_mov_b32_e32 v19, v2
	v_mov_b32_e32 v20, v2
	v_mov_b32_e32 v21, v2
	v_mov_b32_e32 v22, v2
	v_mov_b32_e32 v23, v2
	v_mov_b32_e32 v24, v2
	v_mov_b32_e32 v25, v2
	v_mov_b32_e32 v26, v2
	v_mov_b32_e32 v27, v2
	v_mov_b32_e32 v28, v2
	v_mov_b32_e32 v29, v2
	v_mov_b32_e32 v30, v2
	v_mov_b32_e32 v31, v2
	v_mov_b32_e32 v32, v2
	v_mov_b32_e32 v33, v2
	v_mov_b32_e32 v66, v2
	v_mov_b32_e32 v67, v2
	v_mov_b32_e32 v68, v2
	v_mov_b32_e32 v69, v2
	v_mov_b32_e32 v70, v2
	v_mov_b32_e32 v71, v2
	v_mov_b32_e32 v72, v2
	v_mov_b32_e32 v73, v2
	v_mov_b32_e32 v74, v2
	v_mov_b32_e32 v75, v2
	v_mov_b32_e32 v76, v2
	v_mov_b32_e32 v77, v2
	v_mov_b32_e32 v78, v2
	v_mov_b32_e32 v79, v2
	v_mov_b32_e32 v80, v2
	v_mov_b32_e32 v81, v2
	v_mov_b32_e32 v82, v2
	v_mov_b32_e32 v83, v2
	v_mov_b32_e32 v84, v2
	v_mov_b32_e32 v85, v2
	v_mov_b32_e32 v86, v2
	v_mov_b32_e32 v87, v2
	v_mov_b32_e32 v88, v2
	v_mov_b32_e32 v89, v2
	v_mov_b32_e32 v90, v2
	v_mov_b32_e32 v91, v2
	v_mov_b32_e32 v92, v2
	v_mov_b32_e32 v93, v2
	v_mov_b32_e32 v94, v2
	v_mov_b32_e32 v95, v2
	v_mov_b32_e32 v96, v2
	v_mov_b32_e32 v97, v2
	v_mov_b32_e32 v34, v2
	v_mov_b32_e32 v35, v2
	v_mov_b32_e32 v36, v2
	v_mov_b32_e32 v37, v2
	v_mov_b32_e32 v38, v2
	v_mov_b32_e32 v39, v2
	v_mov_b32_e32 v40, v2
	v_mov_b32_e32 v41, v2
	v_mov_b32_e32 v42, v2
	v_mov_b32_e32 v43, v2
	v_mov_b32_e32 v44, v2
	v_mov_b32_e32 v45, v2
	v_mov_b32_e32 v46, v2
	v_mov_b32_e32 v47, v2
	v_mov_b32_e32 v48, v2
	v_mov_b32_e32 v49, v2
	v_mov_b32_e32 v50, v2
	v_mov_b32_e32 v51, v2
	v_mov_b32_e32 v52, v2
	v_mov_b32_e32 v53, v2
	v_mov_b32_e32 v54, v2
	v_mov_b32_e32 v55, v2
	v_mov_b32_e32 v56, v2
	v_mov_b32_e32 v57, v2
	v_mov_b32_e32 v58, v2
	v_mov_b32_e32 v59, v2
	v_mov_b32_e32 v60, v2
	v_mov_b32_e32 v61, v2
	v_mov_b32_e32 v62, v2
	v_mov_b32_e32 v63, v2
	v_mov_b32_e32 v64, v2
	v_mov_b32_e32 v65, v2
	v_mov_b32_e32 v98, v2
	v_mov_b32_e32 v99, v2
	v_mov_b32_e32 v100, v2
	v_mov_b32_e32 v101, v2
	v_mov_b32_e32 v102, v2
	v_mov_b32_e32 v103, v2
	v_mov_b32_e32 v104, v2
	v_mov_b32_e32 v105, v2
	v_mov_b32_e32 v106, v2
	v_mov_b32_e32 v107, v2
	v_mov_b32_e32 v108, v2
	v_mov_b32_e32 v109, v2
	v_mov_b32_e32 v110, v2
	v_mov_b32_e32 v111, v2
	v_mov_b32_e32 v112, v2
	v_mov_b32_e32 v113, v2
	v_mov_b32_e32 v114, v2
	v_mov_b32_e32 v115, v2
	v_mov_b32_e32 v116, v2
	v_mov_b32_e32 v117, v2
	v_mov_b32_e32 v118, v2
	v_mov_b32_e32 v119, v2
	v_mov_b32_e32 v120, v2
	v_mov_b32_e32 v121, v2
	v_mov_b32_e32 v122, v2
	v_mov_b32_e32 v123, v2
	v_mov_b32_e32 v124, v2
	v_mov_b32_e32 v125, v2
	v_mov_b32_e32 v126, v2
	v_mov_b32_e32 v127, v2
	v_mov_b32_e32 v128, v2
	v_mov_b32_e32 v129, v2

; __global__ void __launch_bounds__(NWAVES * 64, 2) trunk_fwd(Args args) {
	.amdhsa_kernel _Z9trunk_fwd4Args
		.amdhsa_group_segment_fixed_size 0
		.amdhsa_private_segment_fixed_size 0
		.amdhsa_kernarg_size 536
		.amdhsa_user_sgpr_count 2
		.amdhsa_user_sgpr_dispatch_ptr 0
		.amdhsa_user_sgpr_queue_ptr 0
		.amdhsa_user_sgpr_kernarg_segment_ptr 1
		.amdhsa_user_sgpr_dispatch_id 0
		.amdhsa_user_sgpr_kernarg_preload_length 0
		.amdhsa_user_sgpr_kernarg_preload_offset 0
		.amdhsa_user_sgpr_private_segment_size 0
		.amdhsa_uses_dynamic_stack 0
		.amdhsa_enable_private_segment 0
		.amdhsa_system_sgpr_workgroup_id_x 1
		.amdhsa_system_sgpr_workgroup_id_y 0
		.amdhsa_system_sgpr_workgroup_id_z 0
		.amdhsa_system_sgpr_workgroup_info 0
		.amdhsa_system_vgpr_workitem_id 0
		.amdhsa_next_free_vgpr 256
		.amdhsa_next_free_sgpr 100
		.amdhsa_accum_offset 256
		.amdhsa_reserve_vcc 1
		.amdhsa_float_round_mode_32 0
		.amdhsa_float_round_mode_16_64 0
		.amdhsa_float_denorm_mode_32 3
		.amdhsa_float_denorm_mode_16_64 3
		.amdhsa_dx10_clamp 1
		.amdhsa_ieee_mode 1
		.amdhsa_fp16_overflow 0
		.amdhsa_tg_split 0
		.amdhsa_exception_fp_ieee_invalid_op 0
		.amdhsa_exception_fp_denorm_src 0
		.amdhsa_exception_fp_ieee_div_zero 0
		.amdhsa_exception_fp_ieee_overflow 0
		.amdhsa_exception_fp_ieee_underflow 0
		.amdhsa_exception_fp_ieee_inexact 0
		.amdhsa_exception_int_div_zero 0
	.end_amdhsa_kernel

; __global__ void __launch_bounds__(NWAVES * 64, 2) trunk_fwd(Args args) {
amdhsa.kernels:
  - .agpr_count:     0
    .args:
      - .offset:         0
        .size:           280
        .value_kind:     by_value
      - .offset:         280
        .size:           4
        .value_kind:     hidden_block_count_x
      - .offset:         284
        .size:           4
        .value_kind:     hidden_block_count_y
      - .offset:         288
        .size:           4
        .value_kind:     hidden_block_count_z
      - .offset:         292
        .size:           2
        .value_kind:     hidden_group_size_x
      - .offset:         294
        .size:           2
        .value_kind:     hidden_group_size_y
      - .offset:         296
        .size:           2
        .value_kind:     hidden_group_size_z
      - .offset:         298
        .size:           2
        .value_kind:     hidden_remainder_x
      - .offset:         300
        .size:           2
        .value_kind:     hidden_remainder_y
      - .offset:         302
        .size:           2
        .value_kind:     hidden_remainder_z
      - .offset:         320
        .size:           8
        .value_kind:     hidden_global_offset_x
      - .offset:         328
        .size:           8
        .value_kind:     hidden_global_offset_y
      - .offset:         336
        .size:           8
        .value_kind:     hidden_global_offset_z
      - .offset:         344
        .size:           2
        .value_kind:     hidden_grid_dims
      - .offset:         400
        .size:           4
        .value_kind:     hidden_dynamic_lds_size
    .group_segment_fixed_size: 0
    .kernarg_segment_align: 8
    .kernarg_segment_size: 536
    .language:       OpenCL C
    .language_version:
      - 2
      - 0
    .max_flat_workgroup_size: 512
    .name:           _Z9trunk_fwd4Args
    .private_segment_fixed_size: 0
    .sgpr_count:     106
    .sgpr_spill_count: 209
    .symbol:         _Z9trunk_fwd4Args.kd
    .uniform_work_group_size: 1
    .uses_dynamic_stack: false
    .vgpr_count:     256
    .vgpr_spill_count: 0
    .wavefront_size: 64
